# phase sp3 static and wave-granular: chain tiles and S5 output tasks assigned per wave with no tickets or workgroup barriers; only the SGU items stay in the compiler loop (one static item per workgroup
# speedup vs baseline: 1.3365x; 1.0259x over previous
.Lssd_back:
	s_cmp_eq_u32 s5, 3
	s_cbranch_scc1 .Lsp3_entry

.Lsp3_entry:
	v_lshrrev_b32_e32 v0, 6, v206
	s_nop 0
	v_readfirstlane_b32 s40, v0
	s_cmp_lt_u32 s40, 4
	s_cbranch_scc1 .Lsp3_s5o
	s_lshr_b32 s35, s63, 4
	s_lshl_b32 s35, s35, 3
	s_and_b32 s43, s63, 7
	s_or_b32 s35, s35, s43
	s_bfe_u32 s43, s63, 0x10003
	s_lshl_b32 s43, s43, 2
	s_add_u32 s43, s43, s40
	s_sub_u32 s43, s43, 4
	v_and_b32_e32 v165, 63, v206
	v_lshrrev_b32_e32 v166, 6, v206
	v_and_b32_e32 v0, 15, v165
	v_readfirstlane_b32 s40, v166
	v_lshrrev_b32_e32 v1, 4, v165
	s_lshr_b32 s38, s35, 2
	s_and_b32 s42, s35, 3
	s_lshr_b32 s100, s38, 4
	s_lshl_b32 s101, s100, 3
	s_add_u32 s101, s101, 32
	s_bfe_u32 s41, s38, 0x30001
	s_and_b32 s39, s38, 1
	s_lshl_b32 s52, s100, 1
	s_add_u32 s52, s52, s36
	s_lshl_b32 s52, s52, 1
	s_add_u32 s52, s52, s39
	s_lshl_b32 s52, s52, 3
	s_add_u32 s52, s52, s41
	s_add_u32 s100, s101, 7
	s_cmp_eq_u32 s39, 0
	s_cselect_b32 s101, s101, s100
	s_cselect_b32 s92, 0, -1
	s_mov_b32 s98, 0xfffe0000
	s_cselect_b32 s98, 0x20000, s98
	s_mov_b32 s99, 0xffff0000
	s_cselect_b32 s99, 0x10000, s99
	s_mov_b32 s50, 0xfffc0000
	s_cselect_b32 s50, 0x40000, s50
	s_mov_b32 s51, 0xffffe000
	s_cselect_b32 s51, 0x2000, s51
	s_lshl_b32 s100, s101, 3
	s_add_u32 s100, s100, s41
	s_lshl_b32 s100, s100, 14
	s_lshl_b32 s53, s42, 12
	s_add_u32 s100, s100, s53
	s_add_u32 s100, s100, 0xc184000
	s_add_u32 s44, s96, s100
	s_addc_u32 s45, s97, 0
	s_lshl_b32 s100, s101, 1
	s_lshr_b32 s53, s41, 2
	s_add_u32 s100, s100, s53
	s_lshl_b32 s100, s100, 15
	s_lshl_b32 s53, s43, 12
	s_add_u32 s100, s100, s53
	s_add_u32 s100, s100, 0xbe84000
	s_add_u32 s46, s96, s100
	s_addc_u32 s47, s97, 0
	s_lshl_b32 s100, s101, 1
	s_add_u32 s100, s100, s39
	s_lshl_b32 s100, s100, 3
	s_add_u32 s100, s100, s41
	s_lshl_b32 s53, s100, 14
	s_lshl_b32 s59, s42, 12
	s_add_u32 s53, s53, s59
	s_lshl_b32 s59, s43, 5
	s_add_u32 s53, s53, s59
	s_add_u32 s53, s53, 0xac84000
	s_add_u32 s48, s96, s53
	s_addc_u32 s49, s97, 0
	s_lshl_b32 s100, s100, 9
	s_add_u32 s53, s100, 0xcae4000
	s_add_u32 s58, s96, s53
	s_addc_u32 s59, s97, 0
	s_cmp_eq_u32 s39, 0
	s_cselect_b32 s53, 0x1fc, 0
	s_add_u32 s58, s58, s53
	s_addc_u32 s59, s59, 0
	global_load_dword v171, v2, s[58:59]
	s_add_u32 s58, s58, s51
	s_addc_u32 s59, s59, s92
	global_load_dword v172, v2, s[58:59]
	s_add_u32 s58, s58, s51
	s_addc_u32 s59, s59, s92
	global_load_dword v173, v2, s[58:59]
	s_add_u32 s58, s58, s51
	s_addc_u32 s59, s59, s92
	global_load_dword v174, v2, s[58:59]
	s_add_u32 s58, s58, s51
	s_addc_u32 s59, s59, s92
	global_load_dword v175, v2, s[58:59]
	s_add_u32 s58, s58, s51
	s_addc_u32 s59, s59, s92
	global_load_dword v176, v2, s[58:59]
	s_add_u32 s58, s58, s51
	s_addc_u32 s59, s59, s92
	global_load_dword v177, v2, s[58:59]
	s_add_u32 s58, s58, s51
	s_addc_u32 s59, s59, s92
	global_load_dword v178, v2, s[58:59]
	s_add_u32 s53, s100, 0xcb44000
	s_add_u32 s58, s96, s53
	s_addc_u32 s59, s97, 0
	s_cmp_eq_u32 s39, 0
	s_cbranch_scc1 .Lch_slat_fw
	s_sub_u32 s58, s58, 0x2000
	s_subb_u32 s59, s59, 0
.Lch_slat_fw:
	v_lshrrev_b32_e32 v167, 5, v165
	v_and_b32_e32 v168, 31, v165
	v_lshlrev_b32_e32 v167, 13, v167
	v_lshl_add_u32 v167, v168, 4, v167
	s_mul_i32 s53, s40, 16896
	s_lshl_b32 s100, s51, 1
	s_add_u32 m0, s53, 0x0
	s_nop 0
	global_load_lds_dwordx4 v167, s[58:59]
	s_add_u32 s58, s58, s100
	s_addc_u32 s59, s59, s92
	s_add_u32 m0, s53, 0x400
	s_nop 0
	global_load_lds_dwordx4 v167, s[58:59]
	s_add_u32 s58, s58, s100
	s_addc_u32 s59, s59, s92
	s_add_u32 m0, s53, 0x800
	s_nop 0
	global_load_lds_dwordx4 v167, s[58:59]
	s_add_u32 s58, s58, s100
	s_addc_u32 s59, s59, s92
	s_add_u32 m0, s53, 0xc00
	s_nop 0
	global_load_lds_dwordx4 v167, s[58:59]
	v_lshlrev_b32_e32 v160, 8, v0
	v_lshl_add_u32 v160, v1, 4, v160
	v_lshlrev_b32_e32 v161, 11, v1
	v_lshl_add_u32 v161, v0, 2, v161
	v_lshrrev_b32_e32 v162, 1, v161
	v_lshl_add_u32 v163, v1, 5, s53
	s_lshl_b32 s100, s52, 15
	s_lshl_b32 s53, s42, 13
	s_add_u32 s100, s100, s53
	s_lshl_b32 s53, s43, 6
	s_add_u32 s100, s100, s53
	s_add_u32 s58, s72, s100
	s_addc_u32 s59, s73, 0
	global_load_dword v156, v161, s[58:59]
	global_load_dword v157, v161, s[58:59] offset:512
	global_load_dword v158, v161, s[58:59] offset:1024
	global_load_dword v159, v161, s[58:59] offset:1536
	global_load_dwordx4 v[4:7], v160, s[44:45]
	global_load_dwordx4 v[8:11], v160, s[44:45] offset:64
	global_load_dwordx4 v[12:15], v160, s[44:45] offset:128
	global_load_dwordx4 v[16:19], v160, s[44:45] offset:192
	global_load_dwordx4 v[20:23], v160, s[46:47]
	global_load_dwordx4 v[24:27], v160, s[46:47] offset:64
	global_load_dwordx4 v[28:31], v160, s[46:47] offset:128
	global_load_dwordx4 v[32:35], v160, s[46:47] offset:192
	s_add_u32 s44, s44, s98
	s_addc_u32 s45, s45, s92
	s_add_u32 s46, s46, s99
	s_addc_u32 s47, s47, s92
	global_load_dwordx4 v[36:39], v160, s[44:45]
	global_load_dwordx4 v[40:43], v160, s[44:45] offset:64
	global_load_dwordx4 v[44:47], v160, s[44:45] offset:128
	global_load_dwordx4 v[48:51], v160, s[44:45] offset:192
	global_load_dwordx4 v[52:55], v160, s[46:47]
	global_load_dwordx4 v[56:59], v160, s[46:47] offset:64
	global_load_dwordx4 v[60:63], v160, s[46:47] offset:128
	global_load_dwordx4 v[64:67], v160, s[46:47] offset:192
	s_add_u32 s44, s44, s98
	s_addc_u32 s45, s45, s92
	s_add_u32 s46, s46, s99
	s_addc_u32 s47, s47, s92
	global_load_dwordx4 v[68:71], v160, s[44:45]
	global_load_dwordx4 v[72:75], v160, s[44:45] offset:64
	global_load_dwordx4 v[76:79], v160, s[44:45] offset:128
	global_load_dwordx4 v[80:83], v160, s[44:45] offset:192
	global_load_dwordx4 v[84:87], v160, s[46:47]
	global_load_dwordx4 v[88:91], v160, s[46:47] offset:64
	global_load_dwordx4 v[92:95], v160, s[46:47] offset:128
	global_load_dwordx4 v[96:99], v160, s[46:47] offset:192
	s_add_u32 s44, s44, s98
	s_addc_u32 s45, s45, s92
	s_add_u32 s46, s46, s99
	s_addc_u32 s47, s47, s92
	global_load_dwordx4 v[100:103], v160, s[44:45]
	global_load_dwordx4 v[104:107], v160, s[44:45] offset:64
	global_load_dwordx4 v[108:111], v160, s[44:45] offset:128
	global_load_dwordx4 v[112:115], v160, s[44:45] offset:192
	global_load_dwordx4 v[116:119], v160, s[46:47]
	global_load_dwordx4 v[120:123], v160, s[46:47] offset:64
	global_load_dwordx4 v[124:127], v160, s[46:47] offset:128
	global_load_dwordx4 v[128:131], v160, s[46:47] offset:192
	s_add_u32 s44, s44, s98
	s_addc_u32 s45, s45, s92
	s_add_u32 s46, s46, s99
	s_addc_u32 s47, s47, s92
	s_waitcnt vmcnt(24)
	s_xor_b32 s100, s39, 0
	s_lshl_b32 s100, s100, 9
	v_add_u32_e32 v170, s100, v163
	s_nop 0
	ds_read_b128 v[132:135], v170
	ds_read_b128 v[136:139], v170 offset:16
	v_bfe_u32 v165, v156, 16, 1
	v_add3_u32 v165, v156, v165, s27
	global_store_short_d16_hi v162, v165, s[48:49] offset:0
	v_bfe_u32 v166, v157, 16, 1
	v_add3_u32 v166, v157, v166, s27
	global_store_short_d16_hi v162, v166, s[48:49] offset:256
	v_bfe_u32 v167, v158, 16, 1
	v_add3_u32 v167, v158, v167, s27
	global_store_short_d16_hi v162, v167, s[48:49] offset:512
	v_bfe_u32 v168, v159, 16, 1
	v_add3_u32 v168, v159, v168, s27
	global_store_short_d16_hi v162, v168, s[48:49] offset:768
	s_add_u32 s48, s48, s50
	s_addc_u32 s49, s49, s92
	v_mul_f32_e32 v164, 0x3fb8aa3b, v171
	v_exp_f32_e32 v164, v164
	s_nop 0
	v_mul_f32_e32 v156, v156, v164
	v_mul_f32_e32 v157, v157, v164
	v_mul_f32_e32 v158, v158, v164
	v_mul_f32_e32 v159, v159, v164
	ds_read_b128 v[140:143], v170 offset:128
	ds_read_b128 v[144:147], v170 offset:144
	s_waitcnt lgkmcnt(2)
	v_lshlrev_b32_e32 v165, 16, v4
	v_and_b32_e32 v166, s28, v4
	v_mul_f32_e32 v165, v165, v132
	v_mul_f32_e32 v166, v166, v133
	v_cvt_pk_bf16_f32 v148, v165, v166
	v_lshlrev_b32_e32 v165, 16, v5
	v_and_b32_e32 v166, s28, v5
	v_mul_f32_e32 v165, v165, v134
	v_mul_f32_e32 v166, v166, v135
	v_cvt_pk_bf16_f32 v149, v165, v166
	v_lshlrev_b32_e32 v165, 16, v6
	v_and_b32_e32 v166, s28, v6
	v_mul_f32_e32 v165, v165, v136
	v_mul_f32_e32 v166, v166, v137
	v_cvt_pk_bf16_f32 v150, v165, v166
	v_lshlrev_b32_e32 v165, 16, v7
	v_and_b32_e32 v166, s28, v7
	v_mul_f32_e32 v165, v165, v138
	v_mul_f32_e32 v166, v166, v139
	v_cvt_pk_bf16_f32 v151, v165, v166
	s_nop 1
	v_mfma_f32_16x16x32_bf16 v[156:159], v[148:151], v[20:23], v[156:159]
	ds_read_b128 v[132:135], v170 offset:256
	ds_read_b128 v[136:139], v170 offset:272
	s_waitcnt lgkmcnt(2)
	v_lshlrev_b32_e32 v165, 16, v8
	v_and_b32_e32 v166, s28, v8
	v_mul_f32_e32 v165, v165, v140
	v_mul_f32_e32 v166, v166, v141
	v_cvt_pk_bf16_f32 v152, v165, v166
	v_lshlrev_b32_e32 v165, 16, v9
	v_and_b32_e32 v166, s28, v9
	v_mul_f32_e32 v165, v165, v142
	v_mul_f32_e32 v166, v166, v143
	v_cvt_pk_bf16_f32 v153, v165, v166
	v_lshlrev_b32_e32 v165, 16, v10
	v_and_b32_e32 v166, s28, v10
	v_mul_f32_e32 v165, v165, v144
	v_mul_f32_e32 v166, v166, v145
	v_cvt_pk_bf16_f32 v154, v165, v166
	v_lshlrev_b32_e32 v165, 16, v11
	v_and_b32_e32 v166, s28, v11
	v_mul_f32_e32 v165, v165, v146
	v_mul_f32_e32 v166, v166, v147
	v_cvt_pk_bf16_f32 v155, v165, v166
	s_nop 1
	v_mfma_f32_16x16x32_bf16 v[156:159], v[152:155], v[24:27], v[156:159]
	ds_read_b128 v[140:143], v170 offset:384
	ds_read_b128 v[144:147], v170 offset:400
	s_waitcnt lgkmcnt(2)
	v_lshlrev_b32_e32 v165, 16, v12
	v_and_b32_e32 v166, s28, v12
	v_mul_f32_e32 v165, v165, v132
	v_mul_f32_e32 v166, v166, v133
	v_cvt_pk_bf16_f32 v148, v165, v166
	v_lshlrev_b32_e32 v165, 16, v13
	v_and_b32_e32 v166, s28, v13
	v_mul_f32_e32 v165, v165, v134
	v_mul_f32_e32 v166, v166, v135
	v_cvt_pk_bf16_f32 v149, v165, v166
	v_lshlrev_b32_e32 v165, 16, v14
	v_and_b32_e32 v166, s28, v14
	v_mul_f32_e32 v165, v165, v136
	v_mul_f32_e32 v166, v166, v137
	v_cvt_pk_bf16_f32 v150, v165, v166
	v_lshlrev_b32_e32 v165, 16, v15
	v_and_b32_e32 v166, s28, v15
	v_mul_f32_e32 v165, v165, v138
	v_mul_f32_e32 v166, v166, v139
	v_cvt_pk_bf16_f32 v151, v165, v166
	s_nop 1
	v_mfma_f32_16x16x32_bf16 v[156:159], v[148:151], v[28:31], v[156:159]
	s_waitcnt lgkmcnt(0)
	v_lshlrev_b32_e32 v165, 16, v16
	v_and_b32_e32 v166, s28, v16
	v_mul_f32_e32 v165, v165, v140
	v_mul_f32_e32 v166, v166, v141
	v_cvt_pk_bf16_f32 v152, v165, v166
	v_lshlrev_b32_e32 v165, 16, v17
	v_and_b32_e32 v166, s28, v17
	v_mul_f32_e32 v165, v165, v142
	v_mul_f32_e32 v166, v166, v143
	v_cvt_pk_bf16_f32 v153, v165, v166
	v_lshlrev_b32_e32 v165, 16, v18
	v_and_b32_e32 v166, s28, v18
	v_mul_f32_e32 v165, v165, v144
	v_mul_f32_e32 v166, v166, v145
	v_cvt_pk_bf16_f32 v154, v165, v166
	v_lshlrev_b32_e32 v165, 16, v19
	v_and_b32_e32 v166, s28, v19
	v_mul_f32_e32 v165, v165, v146
	v_mul_f32_e32 v166, v166, v147
	v_cvt_pk_bf16_f32 v155, v165, v166
	s_nop 1
	v_mfma_f32_16x16x32_bf16 v[156:159], v[152:155], v[32:35], v[156:159]
	global_load_dwordx4 v[4:7], v160, s[44:45]
	global_load_dwordx4 v[8:11], v160, s[44:45] offset:64
	global_load_dwordx4 v[12:15], v160, s[44:45] offset:128
	global_load_dwordx4 v[16:19], v160, s[44:45] offset:192
	global_load_dwordx4 v[20:23], v160, s[46:47]
	global_load_dwordx4 v[24:27], v160, s[46:47] offset:64
	global_load_dwordx4 v[28:31], v160, s[46:47] offset:128
	global_load_dwordx4 v[32:35], v160, s[46:47] offset:192
	s_add_u32 s44, s44, s98
	s_addc_u32 s45, s45, s92
	s_add_u32 s46, s46, s99
	s_addc_u32 s47, s47, s92
	s_waitcnt vmcnt(28)
	s_xor_b32 s100, s39, 1
	s_lshl_b32 s100, s100, 9
	v_add_u32_e32 v170, s100, v163
	s_nop 0
	ds_read_b128 v[132:135], v170
	ds_read_b128 v[136:139], v170 offset:16
	v_bfe_u32 v165, v156, 16, 1
	v_add3_u32 v165, v156, v165, s27
	global_store_short_d16_hi v162, v165, s[48:49] offset:0
	v_bfe_u32 v166, v157, 16, 1
	v_add3_u32 v166, v157, v166, s27
	global_store_short_d16_hi v162, v166, s[48:49] offset:256
	v_bfe_u32 v167, v158, 16, 1
	v_add3_u32 v167, v158, v167, s27
	global_store_short_d16_hi v162, v167, s[48:49] offset:512
	v_bfe_u32 v168, v159, 16, 1
	v_add3_u32 v168, v159, v168, s27
	global_store_short_d16_hi v162, v168, s[48:49] offset:768
	s_add_u32 s48, s48, s50
	s_addc_u32 s49, s49, s92
	v_mul_f32_e32 v164, 0x3fb8aa3b, v172
	v_exp_f32_e32 v164, v164
	s_nop 0
	v_mul_f32_e32 v156, v156, v164
	v_mul_f32_e32 v157, v157, v164
	v_mul_f32_e32 v158, v158, v164
	v_mul_f32_e32 v159, v159, v164
	ds_read_b128 v[140:143], v170 offset:128
	ds_read_b128 v[144:147], v170 offset:144
	s_waitcnt lgkmcnt(2)
	v_lshlrev_b32_e32 v165, 16, v36
	v_and_b32_e32 v166, s28, v36
	v_mul_f32_e32 v165, v165, v132
	v_mul_f32_e32 v166, v166, v133
	v_cvt_pk_bf16_f32 v148, v165, v166
	v_lshlrev_b32_e32 v165, 16, v37
	v_and_b32_e32 v166, s28, v37
	v_mul_f32_e32 v165, v165, v134
	v_mul_f32_e32 v166, v166, v135
	v_cvt_pk_bf16_f32 v149, v165, v166
	v_lshlrev_b32_e32 v165, 16, v38
	v_and_b32_e32 v166, s28, v38
	v_mul_f32_e32 v165, v165, v136
	v_mul_f32_e32 v166, v166, v137
	v_cvt_pk_bf16_f32 v150, v165, v166
	v_lshlrev_b32_e32 v165, 16, v39
	v_and_b32_e32 v166, s28, v39
	v_mul_f32_e32 v165, v165, v138
	v_mul_f32_e32 v166, v166, v139
	v_cvt_pk_bf16_f32 v151, v165, v166
	s_nop 1
	v_mfma_f32_16x16x32_bf16 v[156:159], v[148:151], v[52:55], v[156:159]
	ds_read_b128 v[132:135], v170 offset:256
	ds_read_b128 v[136:139], v170 offset:272
	s_waitcnt lgkmcnt(2)
	v_lshlrev_b32_e32 v165, 16, v40
	v_and_b32_e32 v166, s28, v40
	v_mul_f32_e32 v165, v165, v140
	v_mul_f32_e32 v166, v166, v141
	v_cvt_pk_bf16_f32 v152, v165, v166
	v_lshlrev_b32_e32 v165, 16, v41
	v_and_b32_e32 v166, s28, v41
	v_mul_f32_e32 v165, v165, v142
	v_mul_f32_e32 v166, v166, v143
	v_cvt_pk_bf16_f32 v153, v165, v166
	v_lshlrev_b32_e32 v165, 16, v42
	v_and_b32_e32 v166, s28, v42
	v_mul_f32_e32 v165, v165, v144
	v_mul_f32_e32 v166, v166, v145
	v_cvt_pk_bf16_f32 v154, v165, v166
	v_lshlrev_b32_e32 v165, 16, v43
	v_and_b32_e32 v166, s28, v43
	v_mul_f32_e32 v165, v165, v146
	v_mul_f32_e32 v166, v166, v147
	v_cvt_pk_bf16_f32 v155, v165, v166
	s_nop 1
	v_mfma_f32_16x16x32_bf16 v[156:159], v[152:155], v[56:59], v[156:159]
	ds_read_b128 v[140:143], v170 offset:384
	ds_read_b128 v[144:147], v170 offset:400
	s_waitcnt lgkmcnt(2)
	v_lshlrev_b32_e32 v165, 16, v44
	v_and_b32_e32 v166, s28, v44
	v_mul_f32_e32 v165, v165, v132
	v_mul_f32_e32 v166, v166, v133
	v_cvt_pk_bf16_f32 v148, v165, v166
	v_lshlrev_b32_e32 v165, 16, v45
	v_and_b32_e32 v166, s28, v45
	v_mul_f32_e32 v165, v165, v134
	v_mul_f32_e32 v166, v166, v135
	v_cvt_pk_bf16_f32 v149, v165, v166
	v_lshlrev_b32_e32 v165, 16, v46
	v_and_b32_e32 v166, s28, v46
	v_mul_f32_e32 v165, v165, v136
	v_mul_f32_e32 v166, v166, v137
	v_cvt_pk_bf16_f32 v150, v165, v166
	v_lshlrev_b32_e32 v165, 16, v47
	v_and_b32_e32 v166, s28, v47
	v_mul_f32_e32 v165, v165, v138
	v_mul_f32_e32 v166, v166, v139
	v_cvt_pk_bf16_f32 v151, v165, v166
	s_nop 1
	v_mfma_f32_16x16x32_bf16 v[156:159], v[148:151], v[60:63], v[156:159]
	s_waitcnt lgkmcnt(0)
	v_lshlrev_b32_e32 v165, 16, v48
	v_and_b32_e32 v166, s28, v48
	v_mul_f32_e32 v165, v165, v140
	v_mul_f32_e32 v166, v166, v141
	v_cvt_pk_bf16_f32 v152, v165, v166
	v_lshlrev_b32_e32 v165, 16, v49
	v_and_b32_e32 v166, s28, v49
	v_mul_f32_e32 v165, v165, v142
	v_mul_f32_e32 v166, v166, v143
	v_cvt_pk_bf16_f32 v153, v165, v166
	v_lshlrev_b32_e32 v165, 16, v50
	v_and_b32_e32 v166, s28, v50
	v_mul_f32_e32 v165, v165, v144
	v_mul_f32_e32 v166, v166, v145
	v_cvt_pk_bf16_f32 v154, v165, v166
	v_lshlrev_b32_e32 v165, 16, v51
	v_and_b32_e32 v166, s28, v51
	v_mul_f32_e32 v165, v165, v146
	v_mul_f32_e32 v166, v166, v147
	v_cvt_pk_bf16_f32 v155, v165, v166
	s_nop 1
	v_mfma_f32_16x16x32_bf16 v[156:159], v[152:155], v[64:67], v[156:159]
	global_load_dwordx4 v[36:39], v160, s[44:45]
	global_load_dwordx4 v[40:43], v160, s[44:45] offset:64
	global_load_dwordx4 v[44:47], v160, s[44:45] offset:128
	global_load_dwordx4 v[48:51], v160, s[44:45] offset:192
	global_load_dwordx4 v[52:55], v160, s[46:47]
	global_load_dwordx4 v[56:59], v160, s[46:47] offset:64
	global_load_dwordx4 v[60:63], v160, s[46:47] offset:128
	global_load_dwordx4 v[64:67], v160, s[46:47] offset:192
	s_add_u32 s44, s44, s98
	s_addc_u32 s45, s45, s92
	s_add_u32 s46, s46, s99
	s_addc_u32 s47, s47, s92
	s_waitcnt vmcnt(32)
	s_xor_b32 s100, s39, 2
	s_lshl_b32 s100, s100, 9
	v_add_u32_e32 v170, s100, v163
	s_nop 0
	ds_read_b128 v[132:135], v170
	ds_read_b128 v[136:139], v170 offset:16
	v_bfe_u32 v165, v156, 16, 1
	v_add3_u32 v165, v156, v165, s27
	global_store_short_d16_hi v162, v165, s[48:49] offset:0
	v_bfe_u32 v166, v157, 16, 1
	v_add3_u32 v166, v157, v166, s27
	global_store_short_d16_hi v162, v166, s[48:49] offset:256
	v_bfe_u32 v167, v158, 16, 1
	v_add3_u32 v167, v158, v167, s27
	global_store_short_d16_hi v162, v167, s[48:49] offset:512
	v_bfe_u32 v168, v159, 16, 1
	v_add3_u32 v168, v159, v168, s27
	global_store_short_d16_hi v162, v168, s[48:49] offset:768
	s_add_u32 s48, s48, s50
	s_addc_u32 s49, s49, s92
	v_mul_f32_e32 v164, 0x3fb8aa3b, v173
	v_exp_f32_e32 v164, v164
	s_nop 0
	v_mul_f32_e32 v156, v156, v164
	v_mul_f32_e32 v157, v157, v164
	v_mul_f32_e32 v158, v158, v164
	v_mul_f32_e32 v159, v159, v164
	ds_read_b128 v[140:143], v170 offset:128
	ds_read_b128 v[144:147], v170 offset:144
	s_waitcnt lgkmcnt(2)
	v_lshlrev_b32_e32 v165, 16, v68
	v_and_b32_e32 v166, s28, v68
	v_mul_f32_e32 v165, v165, v132
	v_mul_f32_e32 v166, v166, v133
	v_cvt_pk_bf16_f32 v148, v165, v166
	v_lshlrev_b32_e32 v165, 16, v69
	v_and_b32_e32 v166, s28, v69
	v_mul_f32_e32 v165, v165, v134
	v_mul_f32_e32 v166, v166, v135
	v_cvt_pk_bf16_f32 v149, v165, v166
	v_lshlrev_b32_e32 v165, 16, v70
	v_and_b32_e32 v166, s28, v70
	v_mul_f32_e32 v165, v165, v136
	v_mul_f32_e32 v166, v166, v137
	v_cvt_pk_bf16_f32 v150, v165, v166
	v_lshlrev_b32_e32 v165, 16, v71
	v_and_b32_e32 v166, s28, v71
	v_mul_f32_e32 v165, v165, v138
	v_mul_f32_e32 v166, v166, v139
	v_cvt_pk_bf16_f32 v151, v165, v166
	s_nop 1
	v_mfma_f32_16x16x32_bf16 v[156:159], v[148:151], v[84:87], v[156:159]
	ds_read_b128 v[132:135], v170 offset:256
	ds_read_b128 v[136:139], v170 offset:272
	s_waitcnt lgkmcnt(2)
	v_lshlrev_b32_e32 v165, 16, v72
	v_and_b32_e32 v166, s28, v72
	v_mul_f32_e32 v165, v165, v140
	v_mul_f32_e32 v166, v166, v141
	v_cvt_pk_bf16_f32 v152, v165, v166
	v_lshlrev_b32_e32 v165, 16, v73
	v_and_b32_e32 v166, s28, v73
	v_mul_f32_e32 v165, v165, v142
	v_mul_f32_e32 v166, v166, v143
	v_cvt_pk_bf16_f32 v153, v165, v166
	v_lshlrev_b32_e32 v165, 16, v74
	v_and_b32_e32 v166, s28, v74
	v_mul_f32_e32 v165, v165, v144
	v_mul_f32_e32 v166, v166, v145
	v_cvt_pk_bf16_f32 v154, v165, v166
	v_lshlrev_b32_e32 v165, 16, v75
	v_and_b32_e32 v166, s28, v75
	v_mul_f32_e32 v165, v165, v146
	v_mul_f32_e32 v166, v166, v147
	v_cvt_pk_bf16_f32 v155, v165, v166
	s_nop 1
	v_mfma_f32_16x16x32_bf16 v[156:159], v[152:155], v[88:91], v[156:159]
	ds_read_b128 v[140:143], v170 offset:384
	ds_read_b128 v[144:147], v170 offset:400
	s_waitcnt lgkmcnt(2)
	v_lshlrev_b32_e32 v165, 16, v76
	v_and_b32_e32 v166, s28, v76
	v_mul_f32_e32 v165, v165, v132
	v_mul_f32_e32 v166, v166, v133
	v_cvt_pk_bf16_f32 v148, v165, v166
	v_lshlrev_b32_e32 v165, 16, v77
	v_and_b32_e32 v166, s28, v77
	v_mul_f32_e32 v165, v165, v134
	v_mul_f32_e32 v166, v166, v135
	v_cvt_pk_bf16_f32 v149, v165, v166
	v_lshlrev_b32_e32 v165, 16, v78
	v_and_b32_e32 v166, s28, v78
	v_mul_f32_e32 v165, v165, v136
	v_mul_f32_e32 v166, v166, v137
	v_cvt_pk_bf16_f32 v150, v165, v166
	v_lshlrev_b32_e32 v165, 16, v79
	v_and_b32_e32 v166, s28, v79
	v_mul_f32_e32 v165, v165, v138
	v_mul_f32_e32 v166, v166, v139
	v_cvt_pk_bf16_f32 v151, v165, v166
	s_nop 1
	v_mfma_f32_16x16x32_bf16 v[156:159], v[148:151], v[92:95], v[156:159]
	s_waitcnt lgkmcnt(0)
	v_lshlrev_b32_e32 v165, 16, v80
	v_and_b32_e32 v166, s28, v80
	v_mul_f32_e32 v165, v165, v140
	v_mul_f32_e32 v166, v166, v141
	v_cvt_pk_bf16_f32 v152, v165, v166
	v_lshlrev_b32_e32 v165, 16, v81
	v_and_b32_e32 v166, s28, v81
	v_mul_f32_e32 v165, v165, v142
	v_mul_f32_e32 v166, v166, v143
	v_cvt_pk_bf16_f32 v153, v165, v166
	v_lshlrev_b32_e32 v165, 16, v82
	v_and_b32_e32 v166, s28, v82
	v_mul_f32_e32 v165, v165, v144
	v_mul_f32_e32 v166, v166, v145
	v_cvt_pk_bf16_f32 v154, v165, v166
	v_lshlrev_b32_e32 v165, 16, v83
	v_and_b32_e32 v166, s28, v83
	v_mul_f32_e32 v165, v165, v146
	v_mul_f32_e32 v166, v166, v147
	v_cvt_pk_bf16_f32 v155, v165, v166
	s_nop 1
	v_mfma_f32_16x16x32_bf16 v[156:159], v[152:155], v[96:99], v[156:159]
	global_load_dwordx4 v[68:71], v160, s[44:45]
	global_load_dwordx4 v[72:75], v160, s[44:45] offset:64
	global_load_dwordx4 v[76:79], v160, s[44:45] offset:128
	global_load_dwordx4 v[80:83], v160, s[44:45] offset:192
	global_load_dwordx4 v[84:87], v160, s[46:47]
	global_load_dwordx4 v[88:91], v160, s[46:47] offset:64
	global_load_dwordx4 v[92:95], v160, s[46:47] offset:128
	global_load_dwordx4 v[96:99], v160, s[46:47] offset:192
	s_add_u32 s44, s44, s98
	s_addc_u32 s45, s45, s92
	s_add_u32 s46, s46, s99
	s_addc_u32 s47, s47, s92
	s_waitcnt vmcnt(36)
	s_xor_b32 s100, s39, 3
	s_lshl_b32 s100, s100, 9
	v_add_u32_e32 v170, s100, v163
	s_nop 0
	ds_read_b128 v[132:135], v170
	ds_read_b128 v[136:139], v170 offset:16
	v_bfe_u32 v165, v156, 16, 1
	v_add3_u32 v165, v156, v165, s27
	global_store_short_d16_hi v162, v165, s[48:49] offset:0
	v_bfe_u32 v166, v157, 16, 1
	v_add3_u32 v166, v157, v166, s27
	global_store_short_d16_hi v162, v166, s[48:49] offset:256
	v_bfe_u32 v167, v158, 16, 1
	v_add3_u32 v167, v158, v167, s27
	global_store_short_d16_hi v162, v167, s[48:49] offset:512
	v_bfe_u32 v168, v159, 16, 1
	v_add3_u32 v168, v159, v168, s27
	global_store_short_d16_hi v162, v168, s[48:49] offset:768
	s_add_u32 s48, s48, s50
	s_addc_u32 s49, s49, s92
	v_mul_f32_e32 v164, 0x3fb8aa3b, v174
	v_exp_f32_e32 v164, v164
	s_nop 0
	v_mul_f32_e32 v156, v156, v164
	v_mul_f32_e32 v157, v157, v164
	v_mul_f32_e32 v158, v158, v164
	v_mul_f32_e32 v159, v159, v164
	ds_read_b128 v[140:143], v170 offset:128
	ds_read_b128 v[144:147], v170 offset:144
	s_waitcnt lgkmcnt(2)
	v_lshlrev_b32_e32 v165, 16, v100
	v_and_b32_e32 v166, s28, v100
	v_mul_f32_e32 v165, v165, v132
	v_mul_f32_e32 v166, v166, v133
	v_cvt_pk_bf16_f32 v148, v165, v166
	v_lshlrev_b32_e32 v165, 16, v101
	v_and_b32_e32 v166, s28, v101
	v_mul_f32_e32 v165, v165, v134
	v_mul_f32_e32 v166, v166, v135
	v_cvt_pk_bf16_f32 v149, v165, v166
	v_lshlrev_b32_e32 v165, 16, v102
	v_and_b32_e32 v166, s28, v102
	v_mul_f32_e32 v165, v165, v136
	v_mul_f32_e32 v166, v166, v137
	v_cvt_pk_bf16_f32 v150, v165, v166
	v_lshlrev_b32_e32 v165, 16, v103
	v_and_b32_e32 v166, s28, v103
	v_mul_f32_e32 v165, v165, v138
	v_mul_f32_e32 v166, v166, v139
	v_cvt_pk_bf16_f32 v151, v165, v166
	s_nop 1
	v_mfma_f32_16x16x32_bf16 v[156:159], v[148:151], v[116:119], v[156:159]
	ds_read_b128 v[132:135], v170 offset:256
	ds_read_b128 v[136:139], v170 offset:272
	s_waitcnt lgkmcnt(2)
	v_lshlrev_b32_e32 v165, 16, v104
	v_and_b32_e32 v166, s28, v104
	v_mul_f32_e32 v165, v165, v140
	v_mul_f32_e32 v166, v166, v141
	v_cvt_pk_bf16_f32 v152, v165, v166
	v_lshlrev_b32_e32 v165, 16, v105
	v_and_b32_e32 v166, s28, v105
	v_mul_f32_e32 v165, v165, v142
	v_mul_f32_e32 v166, v166, v143
	v_cvt_pk_bf16_f32 v153, v165, v166
	v_lshlrev_b32_e32 v165, 16, v106
	v_and_b32_e32 v166, s28, v106
	v_mul_f32_e32 v165, v165, v144
	v_mul_f32_e32 v166, v166, v145
	v_cvt_pk_bf16_f32 v154, v165, v166
	v_lshlrev_b32_e32 v165, 16, v107
	v_and_b32_e32 v166, s28, v107
	v_mul_f32_e32 v165, v165, v146
	v_mul_f32_e32 v166, v166, v147
	v_cvt_pk_bf16_f32 v155, v165, v166
	s_nop 1
	v_mfma_f32_16x16x32_bf16 v[156:159], v[152:155], v[120:123], v[156:159]
	ds_read_b128 v[140:143], v170 offset:384
	ds_read_b128 v[144:147], v170 offset:400
	s_waitcnt lgkmcnt(2)
	v_lshlrev_b32_e32 v165, 16, v108
	v_and_b32_e32 v166, s28, v108
	v_mul_f32_e32 v165, v165, v132
	v_mul_f32_e32 v166, v166, v133
	v_cvt_pk_bf16_f32 v148, v165, v166
	v_lshlrev_b32_e32 v165, 16, v109
	v_and_b32_e32 v166, s28, v109
	v_mul_f32_e32 v165, v165, v134
	v_mul_f32_e32 v166, v166, v135
	v_cvt_pk_bf16_f32 v149, v165, v166
	v_lshlrev_b32_e32 v165, 16, v110
	v_and_b32_e32 v166, s28, v110
	v_mul_f32_e32 v165, v165, v136
	v_mul_f32_e32 v166, v166, v137
	v_cvt_pk_bf16_f32 v150, v165, v166
	v_lshlrev_b32_e32 v165, 16, v111
	v_and_b32_e32 v166, s28, v111
	v_mul_f32_e32 v165, v165, v138
	v_mul_f32_e32 v166, v166, v139
	v_cvt_pk_bf16_f32 v151, v165, v166
	s_nop 1
	v_mfma_f32_16x16x32_bf16 v[156:159], v[148:151], v[124:127], v[156:159]
	s_waitcnt lgkmcnt(0)
	v_lshlrev_b32_e32 v165, 16, v112
	v_and_b32_e32 v166, s28, v112
	v_mul_f32_e32 v165, v165, v140
	v_mul_f32_e32 v166, v166, v141
	v_cvt_pk_bf16_f32 v152, v165, v166
	v_lshlrev_b32_e32 v165, 16, v113
	v_and_b32_e32 v166, s28, v113
	v_mul_f32_e32 v165, v165, v142
	v_mul_f32_e32 v166, v166, v143
	v_cvt_pk_bf16_f32 v153, v165, v166
	v_lshlrev_b32_e32 v165, 16, v114
	v_and_b32_e32 v166, s28, v114
	v_mul_f32_e32 v165, v165, v144
	v_mul_f32_e32 v166, v166, v145
	v_cvt_pk_bf16_f32 v154, v165, v166
	v_lshlrev_b32_e32 v165, 16, v115
	v_and_b32_e32 v166, s28, v115
	v_mul_f32_e32 v165, v165, v146
	v_mul_f32_e32 v166, v166, v147
	v_cvt_pk_bf16_f32 v155, v165, v166
	s_nop 1
	v_mfma_f32_16x16x32_bf16 v[156:159], v[152:155], v[128:131], v[156:159]
	global_load_dwordx4 v[100:103], v160, s[44:45]
	global_load_dwordx4 v[104:107], v160, s[44:45] offset:64
	global_load_dwordx4 v[108:111], v160, s[44:45] offset:128
	global_load_dwordx4 v[112:115], v160, s[44:45] offset:192
	global_load_dwordx4 v[116:119], v160, s[46:47]
	global_load_dwordx4 v[120:123], v160, s[46:47] offset:64
	global_load_dwordx4 v[124:127], v160, s[46:47] offset:128
	global_load_dwordx4 v[128:131], v160, s[46:47] offset:192
	s_add_u32 s44, s44, s98
	s_addc_u32 s45, s45, s92
	s_add_u32 s46, s46, s99
	s_addc_u32 s47, s47, s92
	s_waitcnt vmcnt(36)
	s_xor_b32 s100, s39, 4
	s_lshl_b32 s100, s100, 9
	v_add_u32_e32 v170, s100, v163
	s_nop 0
	ds_read_b128 v[132:135], v170
	ds_read_b128 v[136:139], v170 offset:16
	v_bfe_u32 v165, v156, 16, 1
	v_add3_u32 v165, v156, v165, s27
	global_store_short_d16_hi v162, v165, s[48:49] offset:0
	v_bfe_u32 v166, v157, 16, 1
	v_add3_u32 v166, v157, v166, s27
	global_store_short_d16_hi v162, v166, s[48:49] offset:256
	v_bfe_u32 v167, v158, 16, 1
	v_add3_u32 v167, v158, v167, s27
	global_store_short_d16_hi v162, v167, s[48:49] offset:512
	v_bfe_u32 v168, v159, 16, 1
	v_add3_u32 v168, v159, v168, s27
	global_store_short_d16_hi v162, v168, s[48:49] offset:768
	s_add_u32 s48, s48, s50
	s_addc_u32 s49, s49, s92
	v_mul_f32_e32 v164, 0x3fb8aa3b, v175
	v_exp_f32_e32 v164, v164
	s_nop 0
	v_mul_f32_e32 v156, v156, v164
	v_mul_f32_e32 v157, v157, v164
	v_mul_f32_e32 v158, v158, v164
	v_mul_f32_e32 v159, v159, v164
	ds_read_b128 v[140:143], v170 offset:128
	ds_read_b128 v[144:147], v170 offset:144
	s_waitcnt lgkmcnt(2)
	v_lshlrev_b32_e32 v165, 16, v4
	v_and_b32_e32 v166, s28, v4
	v_mul_f32_e32 v165, v165, v132
	v_mul_f32_e32 v166, v166, v133
	v_cvt_pk_bf16_f32 v148, v165, v166
	v_lshlrev_b32_e32 v165, 16, v5
	v_and_b32_e32 v166, s28, v5
	v_mul_f32_e32 v165, v165, v134
	v_mul_f32_e32 v166, v166, v135
	v_cvt_pk_bf16_f32 v149, v165, v166
	v_lshlrev_b32_e32 v165, 16, v6
	v_and_b32_e32 v166, s28, v6
	v_mul_f32_e32 v165, v165, v136
	v_mul_f32_e32 v166, v166, v137
	v_cvt_pk_bf16_f32 v150, v165, v166
	v_lshlrev_b32_e32 v165, 16, v7
	v_and_b32_e32 v166, s28, v7
	v_mul_f32_e32 v165, v165, v138
	v_mul_f32_e32 v166, v166, v139
	v_cvt_pk_bf16_f32 v151, v165, v166
	s_nop 1
	v_mfma_f32_16x16x32_bf16 v[156:159], v[148:151], v[20:23], v[156:159]
	ds_read_b128 v[132:135], v170 offset:256
	ds_read_b128 v[136:139], v170 offset:272
	s_waitcnt lgkmcnt(2)
	v_lshlrev_b32_e32 v165, 16, v8
	v_and_b32_e32 v166, s28, v8
	v_mul_f32_e32 v165, v165, v140
	v_mul_f32_e32 v166, v166, v141
	v_cvt_pk_bf16_f32 v152, v165, v166
	v_lshlrev_b32_e32 v165, 16, v9
	v_and_b32_e32 v166, s28, v9
	v_mul_f32_e32 v165, v165, v142
	v_mul_f32_e32 v166, v166, v143
	v_cvt_pk_bf16_f32 v153, v165, v166
	v_lshlrev_b32_e32 v165, 16, v10
	v_and_b32_e32 v166, s28, v10
	v_mul_f32_e32 v165, v165, v144
	v_mul_f32_e32 v166, v166, v145
	v_cvt_pk_bf16_f32 v154, v165, v166
	v_lshlrev_b32_e32 v165, 16, v11
	v_and_b32_e32 v166, s28, v11
	v_mul_f32_e32 v165, v165, v146
	v_mul_f32_e32 v166, v166, v147
	v_cvt_pk_bf16_f32 v155, v165, v166
	s_nop 1
	v_mfma_f32_16x16x32_bf16 v[156:159], v[152:155], v[24:27], v[156:159]
	ds_read_b128 v[140:143], v170 offset:384
	ds_read_b128 v[144:147], v170 offset:400
	s_waitcnt lgkmcnt(2)
	v_lshlrev_b32_e32 v165, 16, v12
	v_and_b32_e32 v166, s28, v12
	v_mul_f32_e32 v165, v165, v132
	v_mul_f32_e32 v166, v166, v133
	v_cvt_pk_bf16_f32 v148, v165, v166
	v_lshlrev_b32_e32 v165, 16, v13
	v_and_b32_e32 v166, s28, v13
	v_mul_f32_e32 v165, v165, v134
	v_mul_f32_e32 v166, v166, v135
	v_cvt_pk_bf16_f32 v149, v165, v166
	v_lshlrev_b32_e32 v165, 16, v14
	v_and_b32_e32 v166, s28, v14
	v_mul_f32_e32 v165, v165, v136
	v_mul_f32_e32 v166, v166, v137
	v_cvt_pk_bf16_f32 v150, v165, v166
	v_lshlrev_b32_e32 v165, 16, v15
	v_and_b32_e32 v166, s28, v15
	v_mul_f32_e32 v165, v165, v138
	v_mul_f32_e32 v166, v166, v139
	v_cvt_pk_bf16_f32 v151, v165, v166
	s_nop 1
	v_mfma_f32_16x16x32_bf16 v[156:159], v[148:151], v[28:31], v[156:159]
	s_waitcnt lgkmcnt(0)
	v_lshlrev_b32_e32 v165, 16, v16
	v_and_b32_e32 v166, s28, v16
	v_mul_f32_e32 v165, v165, v140
	v_mul_f32_e32 v166, v166, v141
	v_cvt_pk_bf16_f32 v152, v165, v166
	v_lshlrev_b32_e32 v165, 16, v17
	v_and_b32_e32 v166, s28, v17
	v_mul_f32_e32 v165, v165, v142
	v_mul_f32_e32 v166, v166, v143
	v_cvt_pk_bf16_f32 v153, v165, v166
	v_lshlrev_b32_e32 v165, 16, v18
	v_and_b32_e32 v166, s28, v18
	v_mul_f32_e32 v165, v165, v144
	v_mul_f32_e32 v166, v166, v145
	v_cvt_pk_bf16_f32 v154, v165, v166
	v_lshlrev_b32_e32 v165, 16, v19
	v_and_b32_e32 v166, s28, v19
	v_mul_f32_e32 v165, v165, v146
	v_mul_f32_e32 v166, v166, v147
	v_cvt_pk_bf16_f32 v155, v165, v166
	s_nop 1
	v_mfma_f32_16x16x32_bf16 v[156:159], v[152:155], v[32:35], v[156:159]
	s_nop 7
	s_waitcnt vmcnt(28)
	s_xor_b32 s100, s39, 5
	s_lshl_b32 s100, s100, 9
	v_add_u32_e32 v170, s100, v163
	s_nop 0
	ds_read_b128 v[132:135], v170
	ds_read_b128 v[136:139], v170 offset:16
	v_bfe_u32 v165, v156, 16, 1
	v_add3_u32 v165, v156, v165, s27
	global_store_short_d16_hi v162, v165, s[48:49] offset:0
	v_bfe_u32 v166, v157, 16, 1
	v_add3_u32 v166, v157, v166, s27
	global_store_short_d16_hi v162, v166, s[48:49] offset:256
	v_bfe_u32 v167, v158, 16, 1
	v_add3_u32 v167, v158, v167, s27
	global_store_short_d16_hi v162, v167, s[48:49] offset:512
	v_bfe_u32 v168, v159, 16, 1
	v_add3_u32 v168, v159, v168, s27
	global_store_short_d16_hi v162, v168, s[48:49] offset:768
	s_add_u32 s48, s48, s50
	s_addc_u32 s49, s49, s92
	v_mul_f32_e32 v164, 0x3fb8aa3b, v176
	v_exp_f32_e32 v164, v164
	s_nop 0
	v_mul_f32_e32 v156, v156, v164
	v_mul_f32_e32 v157, v157, v164
	v_mul_f32_e32 v158, v158, v164
	v_mul_f32_e32 v159, v159, v164
	ds_read_b128 v[140:143], v170 offset:128
	ds_read_b128 v[144:147], v170 offset:144
	s_waitcnt lgkmcnt(2)
	v_lshlrev_b32_e32 v165, 16, v36
	v_and_b32_e32 v166, s28, v36
	v_mul_f32_e32 v165, v165, v132
	v_mul_f32_e32 v166, v166, v133
	v_cvt_pk_bf16_f32 v148, v165, v166
	v_lshlrev_b32_e32 v165, 16, v37
	v_and_b32_e32 v166, s28, v37
	v_mul_f32_e32 v165, v165, v134
	v_mul_f32_e32 v166, v166, v135
	v_cvt_pk_bf16_f32 v149, v165, v166
	v_lshlrev_b32_e32 v165, 16, v38
	v_and_b32_e32 v166, s28, v38
	v_mul_f32_e32 v165, v165, v136
	v_mul_f32_e32 v166, v166, v137
	v_cvt_pk_bf16_f32 v150, v165, v166
	v_lshlrev_b32_e32 v165, 16, v39
	v_and_b32_e32 v166, s28, v39
	v_mul_f32_e32 v165, v165, v138
	v_mul_f32_e32 v166, v166, v139
	v_cvt_pk_bf16_f32 v151, v165, v166
	s_nop 1
	v_mfma_f32_16x16x32_bf16 v[156:159], v[148:151], v[52:55], v[156:159]
	ds_read_b128 v[132:135], v170 offset:256
	ds_read_b128 v[136:139], v170 offset:272
	s_waitcnt lgkmcnt(2)
	v_lshlrev_b32_e32 v165, 16, v40
	v_and_b32_e32 v166, s28, v40
	v_mul_f32_e32 v165, v165, v140
	v_mul_f32_e32 v166, v166, v141
	v_cvt_pk_bf16_f32 v152, v165, v166
	v_lshlrev_b32_e32 v165, 16, v41
	v_and_b32_e32 v166, s28, v41
	v_mul_f32_e32 v165, v165, v142
	v_mul_f32_e32 v166, v166, v143
	v_cvt_pk_bf16_f32 v153, v165, v166
	v_lshlrev_b32_e32 v165, 16, v42
	v_and_b32_e32 v166, s28, v42
	v_mul_f32_e32 v165, v165, v144
	v_mul_f32_e32 v166, v166, v145
	v_cvt_pk_bf16_f32 v154, v165, v166
	v_lshlrev_b32_e32 v165, 16, v43
	v_and_b32_e32 v166, s28, v43
	v_mul_f32_e32 v165, v165, v146
	v_mul_f32_e32 v166, v166, v147
	v_cvt_pk_bf16_f32 v155, v165, v166
	s_nop 1
	v_mfma_f32_16x16x32_bf16 v[156:159], v[152:155], v[56:59], v[156:159]
	ds_read_b128 v[140:143], v170 offset:384
	ds_read_b128 v[144:147], v170 offset:400
	s_waitcnt lgkmcnt(2)
	v_lshlrev_b32_e32 v165, 16, v44
	v_and_b32_e32 v166, s28, v44
	v_mul_f32_e32 v165, v165, v132
	v_mul_f32_e32 v166, v166, v133
	v_cvt_pk_bf16_f32 v148, v165, v166
	v_lshlrev_b32_e32 v165, 16, v45
	v_and_b32_e32 v166, s28, v45
	v_mul_f32_e32 v165, v165, v134
	v_mul_f32_e32 v166, v166, v135
	v_cvt_pk_bf16_f32 v149, v165, v166
	v_lshlrev_b32_e32 v165, 16, v46
	v_and_b32_e32 v166, s28, v46
	v_mul_f32_e32 v165, v165, v136
	v_mul_f32_e32 v166, v166, v137
	v_cvt_pk_bf16_f32 v150, v165, v166
	v_lshlrev_b32_e32 v165, 16, v47
	v_and_b32_e32 v166, s28, v47
	v_mul_f32_e32 v165, v165, v138
	v_mul_f32_e32 v166, v166, v139
	v_cvt_pk_bf16_f32 v151, v165, v166
	s_nop 1
	v_mfma_f32_16x16x32_bf16 v[156:159], v[148:151], v[60:63], v[156:159]
	s_waitcnt lgkmcnt(0)
	v_lshlrev_b32_e32 v165, 16, v48
	v_and_b32_e32 v166, s28, v48
	v_mul_f32_e32 v165, v165, v140
	v_mul_f32_e32 v166, v166, v141
	v_cvt_pk_bf16_f32 v152, v165, v166
	v_lshlrev_b32_e32 v165, 16, v49
	v_and_b32_e32 v166, s28, v49
	v_mul_f32_e32 v165, v165, v142
	v_mul_f32_e32 v166, v166, v143
	v_cvt_pk_bf16_f32 v153, v165, v166
	v_lshlrev_b32_e32 v165, 16, v50
	v_and_b32_e32 v166, s28, v50
	v_mul_f32_e32 v165, v165, v144
	v_mul_f32_e32 v166, v166, v145
	v_cvt_pk_bf16_f32 v154, v165, v166
	v_lshlrev_b32_e32 v165, 16, v51
	v_and_b32_e32 v166, s28, v51
	v_mul_f32_e32 v165, v165, v146
	v_mul_f32_e32 v166, v166, v147
	v_cvt_pk_bf16_f32 v155, v165, v166
	s_nop 1
	v_mfma_f32_16x16x32_bf16 v[156:159], v[152:155], v[64:67], v[156:159]
	s_nop 7
	s_waitcnt vmcnt(20)
	s_xor_b32 s100, s39, 6
	s_lshl_b32 s100, s100, 9
	v_add_u32_e32 v170, s100, v163
	s_nop 0
	ds_read_b128 v[132:135], v170
	ds_read_b128 v[136:139], v170 offset:16
	v_bfe_u32 v165, v156, 16, 1
	v_add3_u32 v165, v156, v165, s27
	global_store_short_d16_hi v162, v165, s[48:49] offset:0
	v_bfe_u32 v166, v157, 16, 1
	v_add3_u32 v166, v157, v166, s27
	global_store_short_d16_hi v162, v166, s[48:49] offset:256
	v_bfe_u32 v167, v158, 16, 1
	v_add3_u32 v167, v158, v167, s27
	global_store_short_d16_hi v162, v167, s[48:49] offset:512
	v_bfe_u32 v168, v159, 16, 1
	v_add3_u32 v168, v159, v168, s27
	global_store_short_d16_hi v162, v168, s[48:49] offset:768
	s_add_u32 s48, s48, s50
	s_addc_u32 s49, s49, s92
	v_mul_f32_e32 v164, 0x3fb8aa3b, v177
	v_exp_f32_e32 v164, v164
	s_nop 0
	v_mul_f32_e32 v156, v156, v164
	v_mul_f32_e32 v157, v157, v164
	v_mul_f32_e32 v158, v158, v164
	v_mul_f32_e32 v159, v159, v164
	ds_read_b128 v[140:143], v170 offset:128
	ds_read_b128 v[144:147], v170 offset:144
	s_waitcnt lgkmcnt(2)
	v_lshlrev_b32_e32 v165, 16, v68
	v_and_b32_e32 v166, s28, v68
	v_mul_f32_e32 v165, v165, v132
	v_mul_f32_e32 v166, v166, v133
	v_cvt_pk_bf16_f32 v148, v165, v166
	v_lshlrev_b32_e32 v165, 16, v69
	v_and_b32_e32 v166, s28, v69
	v_mul_f32_e32 v165, v165, v134
	v_mul_f32_e32 v166, v166, v135
	v_cvt_pk_bf16_f32 v149, v165, v166
	v_lshlrev_b32_e32 v165, 16, v70
	v_and_b32_e32 v166, s28, v70
	v_mul_f32_e32 v165, v165, v136
	v_mul_f32_e32 v166, v166, v137
	v_cvt_pk_bf16_f32 v150, v165, v166
	v_lshlrev_b32_e32 v165, 16, v71
	v_and_b32_e32 v166, s28, v71
	v_mul_f32_e32 v165, v165, v138
	v_mul_f32_e32 v166, v166, v139
	v_cvt_pk_bf16_f32 v151, v165, v166
	s_nop 1
	v_mfma_f32_16x16x32_bf16 v[156:159], v[148:151], v[84:87], v[156:159]
	ds_read_b128 v[132:135], v170 offset:256
	ds_read_b128 v[136:139], v170 offset:272
	s_waitcnt lgkmcnt(2)
	v_lshlrev_b32_e32 v165, 16, v72
	v_and_b32_e32 v166, s28, v72
	v_mul_f32_e32 v165, v165, v140
	v_mul_f32_e32 v166, v166, v141
	v_cvt_pk_bf16_f32 v152, v165, v166
	v_lshlrev_b32_e32 v165, 16, v73
	v_and_b32_e32 v166, s28, v73
	v_mul_f32_e32 v165, v165, v142
	v_mul_f32_e32 v166, v166, v143
	v_cvt_pk_bf16_f32 v153, v165, v166
	v_lshlrev_b32_e32 v165, 16, v74
	v_and_b32_e32 v166, s28, v74
	v_mul_f32_e32 v165, v165, v144
	v_mul_f32_e32 v166, v166, v145
	v_cvt_pk_bf16_f32 v154, v165, v166
	v_lshlrev_b32_e32 v165, 16, v75
	v_and_b32_e32 v166, s28, v75
	v_mul_f32_e32 v165, v165, v146
	v_mul_f32_e32 v166, v166, v147
	v_cvt_pk_bf16_f32 v155, v165, v166
	s_nop 1
	v_mfma_f32_16x16x32_bf16 v[156:159], v[152:155], v[88:91], v[156:159]
	ds_read_b128 v[140:143], v170 offset:384
	ds_read_b128 v[144:147], v170 offset:400
	s_waitcnt lgkmcnt(2)
	v_lshlrev_b32_e32 v165, 16, v76
	v_and_b32_e32 v166, s28, v76
	v_mul_f32_e32 v165, v165, v132
	v_mul_f32_e32 v166, v166, v133
	v_cvt_pk_bf16_f32 v148, v165, v166
	v_lshlrev_b32_e32 v165, 16, v77
	v_and_b32_e32 v166, s28, v77
	v_mul_f32_e32 v165, v165, v134
	v_mul_f32_e32 v166, v166, v135
	v_cvt_pk_bf16_f32 v149, v165, v166
	v_lshlrev_b32_e32 v165, 16, v78
	v_and_b32_e32 v166, s28, v78
	v_mul_f32_e32 v165, v165, v136
	v_mul_f32_e32 v166, v166, v137
	v_cvt_pk_bf16_f32 v150, v165, v166
	v_lshlrev_b32_e32 v165, 16, v79
	v_and_b32_e32 v166, s28, v79
	v_mul_f32_e32 v165, v165, v138
	v_mul_f32_e32 v166, v166, v139
	v_cvt_pk_bf16_f32 v151, v165, v166
	s_nop 1
	v_mfma_f32_16x16x32_bf16 v[156:159], v[148:151], v[92:95], v[156:159]
	s_waitcnt lgkmcnt(0)
	v_lshlrev_b32_e32 v165, 16, v80
	v_and_b32_e32 v166, s28, v80
	v_mul_f32_e32 v165, v165, v140
	v_mul_f32_e32 v166, v166, v141
	v_cvt_pk_bf16_f32 v152, v165, v166
	v_lshlrev_b32_e32 v165, 16, v81
	v_and_b32_e32 v166, s28, v81
	v_mul_f32_e32 v165, v165, v142
	v_mul_f32_e32 v166, v166, v143
	v_cvt_pk_bf16_f32 v153, v165, v166
	v_lshlrev_b32_e32 v165, 16, v82
	v_and_b32_e32 v166, s28, v82
	v_mul_f32_e32 v165, v165, v144
	v_mul_f32_e32 v166, v166, v145
	v_cvt_pk_bf16_f32 v154, v165, v166
	v_lshlrev_b32_e32 v165, 16, v83
	v_and_b32_e32 v166, s28, v83
	v_mul_f32_e32 v165, v165, v146
	v_mul_f32_e32 v166, v166, v147
	v_cvt_pk_bf16_f32 v155, v165, v166
	s_nop 1
	v_mfma_f32_16x16x32_bf16 v[156:159], v[152:155], v[96:99], v[156:159]
	s_nop 7
	s_waitcnt vmcnt(12)
	s_xor_b32 s100, s39, 7
	s_lshl_b32 s100, s100, 9
	v_add_u32_e32 v170, s100, v163
	s_nop 0
	ds_read_b128 v[132:135], v170
	ds_read_b128 v[136:139], v170 offset:16
	v_bfe_u32 v165, v156, 16, 1
	v_add3_u32 v165, v156, v165, s27
	global_store_short_d16_hi v162, v165, s[48:49] offset:0
	v_bfe_u32 v166, v157, 16, 1
	v_add3_u32 v166, v157, v166, s27
	global_store_short_d16_hi v162, v166, s[48:49] offset:256
	v_bfe_u32 v167, v158, 16, 1
	v_add3_u32 v167, v158, v167, s27
	global_store_short_d16_hi v162, v167, s[48:49] offset:512
	v_bfe_u32 v168, v159, 16, 1
	v_add3_u32 v168, v159, v168, s27
	global_store_short_d16_hi v162, v168, s[48:49] offset:768
	s_add_u32 s48, s48, s50
	s_addc_u32 s49, s49, s92
	v_mul_f32_e32 v164, 0x3fb8aa3b, v178
	v_exp_f32_e32 v164, v164
	s_nop 0
	v_mul_f32_e32 v156, v156, v164
	v_mul_f32_e32 v157, v157, v164
	v_mul_f32_e32 v158, v158, v164
	v_mul_f32_e32 v159, v159, v164
	ds_read_b128 v[140:143], v170 offset:128
	ds_read_b128 v[144:147], v170 offset:144
	s_waitcnt lgkmcnt(2)
	v_lshlrev_b32_e32 v165, 16, v100
	v_and_b32_e32 v166, s28, v100
	v_mul_f32_e32 v165, v165, v132
	v_mul_f32_e32 v166, v166, v133
	v_cvt_pk_bf16_f32 v148, v165, v166
	v_lshlrev_b32_e32 v165, 16, v101
	v_and_b32_e32 v166, s28, v101
	v_mul_f32_e32 v165, v165, v134
	v_mul_f32_e32 v166, v166, v135
	v_cvt_pk_bf16_f32 v149, v165, v166
	v_lshlrev_b32_e32 v165, 16, v102
	v_and_b32_e32 v166, s28, v102
	v_mul_f32_e32 v165, v165, v136
	v_mul_f32_e32 v166, v166, v137
	v_cvt_pk_bf16_f32 v150, v165, v166
	v_lshlrev_b32_e32 v165, 16, v103
	v_and_b32_e32 v166, s28, v103
	v_mul_f32_e32 v165, v165, v138
	v_mul_f32_e32 v166, v166, v139
	v_cvt_pk_bf16_f32 v151, v165, v166
	s_nop 1
	v_mfma_f32_16x16x32_bf16 v[156:159], v[148:151], v[116:119], v[156:159]
	ds_read_b128 v[132:135], v170 offset:256
	ds_read_b128 v[136:139], v170 offset:272
	s_waitcnt lgkmcnt(2)
	v_lshlrev_b32_e32 v165, 16, v104
	v_and_b32_e32 v166, s28, v104
	v_mul_f32_e32 v165, v165, v140
	v_mul_f32_e32 v166, v166, v141
	v_cvt_pk_bf16_f32 v152, v165, v166
	v_lshlrev_b32_e32 v165, 16, v105
	v_and_b32_e32 v166, s28, v105
	v_mul_f32_e32 v165, v165, v142
	v_mul_f32_e32 v166, v166, v143
	v_cvt_pk_bf16_f32 v153, v165, v166
	v_lshlrev_b32_e32 v165, 16, v106
	v_and_b32_e32 v166, s28, v106
	v_mul_f32_e32 v165, v165, v144
	v_mul_f32_e32 v166, v166, v145
	v_cvt_pk_bf16_f32 v154, v165, v166
	v_lshlrev_b32_e32 v165, 16, v107
	v_and_b32_e32 v166, s28, v107
	v_mul_f32_e32 v165, v165, v146
	v_mul_f32_e32 v166, v166, v147
	v_cvt_pk_bf16_f32 v155, v165, v166
	s_nop 1
	v_mfma_f32_16x16x32_bf16 v[156:159], v[152:155], v[120:123], v[156:159]
	ds_read_b128 v[140:143], v170 offset:384
	ds_read_b128 v[144:147], v170 offset:400
	s_waitcnt lgkmcnt(2)
	v_lshlrev_b32_e32 v165, 16, v108
	v_and_b32_e32 v166, s28, v108
	v_mul_f32_e32 v165, v165, v132
	v_mul_f32_e32 v166, v166, v133
	v_cvt_pk_bf16_f32 v148, v165, v166
	v_lshlrev_b32_e32 v165, 16, v109
	v_and_b32_e32 v166, s28, v109
	v_mul_f32_e32 v165, v165, v134
	v_mul_f32_e32 v166, v166, v135
	v_cvt_pk_bf16_f32 v149, v165, v166
	v_lshlrev_b32_e32 v165, 16, v110
	v_and_b32_e32 v166, s28, v110
	v_mul_f32_e32 v165, v165, v136
	v_mul_f32_e32 v166, v166, v137
	v_cvt_pk_bf16_f32 v150, v165, v166
	v_lshlrev_b32_e32 v165, 16, v111
	v_and_b32_e32 v166, s28, v111
	v_mul_f32_e32 v165, v165, v138
	v_mul_f32_e32 v166, v166, v139
	v_cvt_pk_bf16_f32 v151, v165, v166
	s_nop 1
	v_mfma_f32_16x16x32_bf16 v[156:159], v[148:151], v[124:127], v[156:159]
	s_waitcnt lgkmcnt(0)
	v_lshlrev_b32_e32 v165, 16, v112
	v_and_b32_e32 v166, s28, v112
	v_mul_f32_e32 v165, v165, v140
	v_mul_f32_e32 v166, v166, v141
	v_cvt_pk_bf16_f32 v152, v165, v166
	v_lshlrev_b32_e32 v165, 16, v113
	v_and_b32_e32 v166, s28, v113
	v_mul_f32_e32 v165, v165, v142
	v_mul_f32_e32 v166, v166, v143
	v_cvt_pk_bf16_f32 v153, v165, v166
	v_lshlrev_b32_e32 v165, 16, v114
	v_and_b32_e32 v166, s28, v114
	v_mul_f32_e32 v165, v165, v144
	v_mul_f32_e32 v166, v166, v145
	v_cvt_pk_bf16_f32 v154, v165, v166
	v_lshlrev_b32_e32 v165, 16, v115
	v_and_b32_e32 v166, s28, v115
	v_mul_f32_e32 v165, v165, v146
	v_mul_f32_e32 v166, v166, v147
	v_cvt_pk_bf16_f32 v155, v165, v166
	s_nop 1
	v_mfma_f32_16x16x32_bf16 v[156:159], v[152:155], v[128:131], v[156:159]
	s_nop 7
	s_branch .Lsp3_s5o
.Lsp3_s5o:
	v_and_b32_e32 v3, 63, v206
	v_lshrrev_b32_e32 v184, 6, v206
	v_and_b32_e32 v4, 15, v3
	v_readfirstlane_b32 s40, v184
	v_lshrrev_b32_e32 v5, 4, v3
	s_lshl_b32 s41, s63, 3
	s_add_u32 s41, s41, s40
	s_mul_i32 s42, s40, 16896
	v_mul_u32_u24_e32 v6, 2112, v5
	v_lshl_add_u32 v6, v4, 2, v6
	v_add_u32_e32 v6, s42, v6
	v_lshl_add_u32 v7, v3, 3, 0
	v_add_u32_e32 v7, s42, v7
	v_and_b32_e32 v8, 1, v5
	v_lshlrev_b32_e32 v8, 4, v8
	v_lshl_add_u32 v8, v4, 5, v8
	v_lshlrev_b32_e32 v9, 5, v3
	v_lshlrev_b32_e32 v10, 3, v3
	v_mul_u32_u24_e32 v13, 528, v4
	v_lshl_add_u32 v13, v5, 5, v13
	v_add_u32_e32 v13, s42, v13
	v_lshlrev_b32_e32 v14, 8, v4
	v_lshl_add_u32 v14, v5, 4, v14
	s_lshl_b32 s100, s63, 2
	s_add_u32 s100, s100, s40
	s_add_u32 s100, s100, 0x800
	s_cmp_lt_u32 s40, 4
	s_cselect_b32 s43, 2, 1
	s_cselect_b32 s100, s100, s41
.Ls5o_task:
	s_lshr_b32 s98, s100, 4
	s_and_b32 s99, s100, 15
	s_cmpk_lt_u32 s98, 0x80
	s_cbranch_scc1 .Ls5o_ctx
	s_sub_u32 s100, s98, 0x80
	s_lshr_b32 s101, s100, 5
	s_and_b32 s38, s100, 31
	s_movk_i32 s39, 32
	s_lshl_b32 s54, s101, 5
	s_add_u32 s54, s54, 0x80
	s_add_u32 s47, s101, 16
	s_lshl_b32 s101, s101, 10
	s_lshl_b32 s100, s38, 1
	s_add_u32 s100, s100, s101
	s_add_u32 s100, s100, 0x1000
	s_mov_b32 s52, 0x91000
	s_movk_i32 s53, 0x2440
	s_mov_b32 s92, 0x8000
	s_movk_i32 s34, 0x200
	s_mov_b32 s55, 1
	s_branch .Ls5o_rows
.Ls5o_ctx:
	s_lshr_b32 s47, s98, 3
	s_and_b32 s38, s98, 7
	s_movk_i32 s39, 8
	s_lshl_b32 s54, s47, 3
	s_lshl_b32 s100, s98, 5
	s_movk_i32 s52, 0x2440
	s_mov_b32 s53, 0x24400
	s_movk_i32 s92, 0x200
	s_movk_i32 s34, 0x2000
	s_mov_b32 s55, 0

.Ls5o_nofinal:
	s_waitcnt lgkmcnt(0)
	ds_read_b128 v[132:135], v13 offset:0
	ds_read_b128 v[136:139], v13 offset:16
	ds_read_b128 v[140:143], v13 offset:128
	ds_read_b128 v[144:147], v13 offset:144
	ds_read_b128 v[148:151], v13 offset:256
	ds_read_b128 v[152:155], v13 offset:272
	ds_read_b128 v[156:159], v13 offset:384
	ds_read_b128 v[160:163], v13 offset:400
	s_waitcnt lgkmcnt(6)
	v_cvt_pk_bf16_f32 v186, v132, v133
	v_cvt_pk_bf16_f32 v187, v134, v135
	v_cvt_pk_bf16_f32 v188, v136, v137
	v_cvt_pk_bf16_f32 v189, v138, v139
	s_nop 1
	v_mfma_f32_16x16x32_bf16 v[174:177], v[186:189], v[116:119], v[174:177]
	s_waitcnt lgkmcnt(4)
	v_cvt_pk_bf16_f32 v186, v140, v141
	v_cvt_pk_bf16_f32 v187, v142, v143
	v_cvt_pk_bf16_f32 v188, v144, v145
	v_cvt_pk_bf16_f32 v189, v146, v147
	s_nop 1
	v_mfma_f32_16x16x32_bf16 v[174:177], v[186:189], v[120:123], v[174:177]
	s_waitcnt lgkmcnt(2)
	v_cvt_pk_bf16_f32 v186, v148, v149
	v_cvt_pk_bf16_f32 v187, v150, v151
	v_cvt_pk_bf16_f32 v188, v152, v153
	v_cvt_pk_bf16_f32 v189, v154, v155
	s_nop 1
	v_mfma_f32_16x16x32_bf16 v[174:177], v[186:189], v[124:127], v[174:177]
	s_waitcnt lgkmcnt(0)
	v_cvt_pk_bf16_f32 v186, v156, v157
	v_cvt_pk_bf16_f32 v187, v158, v159
	v_cvt_pk_bf16_f32 v188, v160, v161
	v_cvt_pk_bf16_f32 v189, v162, v163
	s_nop 1
	v_mfma_f32_16x16x32_bf16 v[174:177], v[186:189], v[128:131], v[174:177]
	ds_read_b128 v[132:135], v13 offset:8448
	ds_read_b128 v[136:139], v13 offset:8464
	ds_read_b128 v[140:143], v13 offset:8576
	ds_read_b128 v[144:147], v13 offset:8592
	ds_read_b128 v[148:151], v13 offset:8704
	ds_read_b128 v[152:155], v13 offset:8720
	ds_read_b128 v[156:159], v13 offset:8832
	ds_read_b128 v[160:163], v13 offset:8848
	s_waitcnt lgkmcnt(6)
	v_cvt_pk_bf16_f32 v186, v132, v133
	v_cvt_pk_bf16_f32 v187, v134, v135
	v_cvt_pk_bf16_f32 v188, v136, v137
	v_cvt_pk_bf16_f32 v189, v138, v139
	s_nop 1
	v_mfma_f32_16x16x32_bf16 v[178:181], v[186:189], v[116:119], v[178:181]
	s_waitcnt lgkmcnt(4)
	v_cvt_pk_bf16_f32 v186, v140, v141
	v_cvt_pk_bf16_f32 v187, v142, v143
	v_cvt_pk_bf16_f32 v188, v144, v145
	v_cvt_pk_bf16_f32 v189, v146, v147
	s_nop 1
	v_mfma_f32_16x16x32_bf16 v[178:181], v[186:189], v[120:123], v[178:181]
	s_waitcnt lgkmcnt(2)
	v_cvt_pk_bf16_f32 v186, v148, v149
	v_cvt_pk_bf16_f32 v187, v150, v151
	v_cvt_pk_bf16_f32 v188, v152, v153
	v_cvt_pk_bf16_f32 v189, v154, v155
	s_nop 1
	v_mfma_f32_16x16x32_bf16 v[178:181], v[186:189], v[124:127], v[178:181]
	s_waitcnt lgkmcnt(0)
	v_cvt_pk_bf16_f32 v186, v156, v157
	v_cvt_pk_bf16_f32 v187, v158, v159
	v_cvt_pk_bf16_f32 v188, v160, v161
	v_cvt_pk_bf16_f32 v189, v162, v163
	s_nop 1
	v_mfma_f32_16x16x32_bf16 v[178:181], v[186:189], v[128:131], v[178:181]
	s_add_u32 s56, s56, 1
	s_cmp_lt_u32 s56, 2
	s_cbranch_scc1 .Ls5o_dir
	s_mul_i32 s100, s46, 0x200
	s_lshl_b32 s101, s99, 5
	s_add_u32 s100, s100, s101
	s_add_u32 s100, s100, 0xcea4000
	s_add_u32 s48, s96, s100
	s_addc_u32 s49, s97, 0
	s_lshl_b32 s101, s92, 2
	v_mul_lo_u32 v18, v5, s101
	v_lshl_add_u32 v18, v4, 1, v18
	s_nop 4
	v_fmac_f32_e32 v174, v164, v165
	v_mul_f32_e32 v132, 0x3d372713, v174
	v_mul_f32_e32 v132, v174, v132
	v_fma_f32 v132, v174, v132, v174
	v_mul_f32_e32 v132, 0x3f4c422a, v132
	v_add_f32_e32 v132, v132, v132
	v_mul_f32_e32 v132, 0x3fb8aa3b, v132
	v_exp_f32_e32 v132, v132
	v_mul_f32_e32 v133, 0.5, v174
	v_add_f32_e32 v132, 1.0, v132
	v_div_scale_f32 v134, s[100:101], v132, v132, 2.0
	v_rcp_f32_e32 v135, v134
	s_nop 0
	v_fma_f32 v136, -v134, v135, 1.0
	v_fmac_f32_e32 v135, v136, v135
	v_div_scale_f32 v136, vcc, 2.0, v132, 2.0
	v_mul_f32_e32 v137, v136, v135
	v_fma_f32 v138, -v134, v137, v136
	v_fmac_f32_e32 v137, v138, v135
	v_fma_f32 v134, -v134, v137, v136
	v_div_fmas_f32 v134, v134, v135, v137
	v_div_fixup_f32 v132, v134, v132, 2.0
	v_sub_f32_e32 v132, 1.0, v132
	v_add_f32_e32 v132, 1.0, v132
	v_mul_f32_e32 v132, v133, v132
	v_bfe_u32 v133, v132, 16, 1
	v_add3_u32 v132, v132, v133, s27
	v_mov_b32_e32 v184, v18
	global_store_short_d16_hi v184, v132, s[48:49]
	s_nop 0
	v_fmac_f32_e32 v175, v164, v166
	v_mul_f32_e32 v132, 0x3d372713, v175
	v_mul_f32_e32 v132, v175, v132
	v_fma_f32 v132, v175, v132, v175
	v_mul_f32_e32 v132, 0x3f4c422a, v132
	v_add_f32_e32 v132, v132, v132
	v_mul_f32_e32 v132, 0x3fb8aa3b, v132
	v_exp_f32_e32 v132, v132
	v_mul_f32_e32 v133, 0.5, v175
	v_add_f32_e32 v132, 1.0, v132
	v_div_scale_f32 v134, s[100:101], v132, v132, 2.0
	v_rcp_f32_e32 v135, v134
	s_nop 0
	v_fma_f32 v136, -v134, v135, 1.0
	v_fmac_f32_e32 v135, v136, v135
	v_div_scale_f32 v136, vcc, 2.0, v132, 2.0
	v_mul_f32_e32 v137, v136, v135
	v_fma_f32 v138, -v134, v137, v136
	v_fmac_f32_e32 v137, v138, v135
	v_fma_f32 v134, -v134, v137, v136
	v_div_fmas_f32 v134, v134, v135, v137
	v_div_fixup_f32 v132, v134, v132, 2.0
	v_sub_f32_e32 v132, 1.0, v132
	v_add_f32_e32 v132, 1.0, v132
	v_mul_f32_e32 v132, v133, v132
	v_bfe_u32 v133, v132, 16, 1
	v_add3_u32 v132, v132, v133, s27
	v_add_u32_e32 v184, s92, v184
	global_store_short_d16_hi v184, v132, s[48:49]
	s_nop 0
	v_fmac_f32_e32 v176, v164, v167
	v_mul_f32_e32 v132, 0x3d372713, v176
	v_mul_f32_e32 v132, v176, v132
	v_fma_f32 v132, v176, v132, v176
	v_mul_f32_e32 v132, 0x3f4c422a, v132
	v_add_f32_e32 v132, v132, v132
	v_mul_f32_e32 v132, 0x3fb8aa3b, v132
	v_exp_f32_e32 v132, v132
	v_mul_f32_e32 v133, 0.5, v176
	v_add_f32_e32 v132, 1.0, v132
	v_div_scale_f32 v134, s[100:101], v132, v132, 2.0
	v_rcp_f32_e32 v135, v134
	s_nop 0
	v_fma_f32 v136, -v134, v135, 1.0
	v_fmac_f32_e32 v135, v136, v135
	v_div_scale_f32 v136, vcc, 2.0, v132, 2.0
	v_mul_f32_e32 v137, v136, v135
	v_fma_f32 v138, -v134, v137, v136
	v_fmac_f32_e32 v137, v138, v135
	v_fma_f32 v134, -v134, v137, v136
	v_div_fmas_f32 v134, v134, v135, v137
	v_div_fixup_f32 v132, v134, v132, 2.0
	v_sub_f32_e32 v132, 1.0, v132
	v_add_f32_e32 v132, 1.0, v132
	v_mul_f32_e32 v132, v133, v132
	v_bfe_u32 v133, v132, 16, 1
	v_add3_u32 v132, v132, v133, s27
	v_add_u32_e32 v184, s92, v184
	global_store_short_d16_hi v184, v132, s[48:49]
	s_nop 0
	v_fmac_f32_e32 v177, v164, v168
	v_mul_f32_e32 v132, 0x3d372713, v177
	v_mul_f32_e32 v132, v177, v132
	v_fma_f32 v132, v177, v132, v177
	v_mul_f32_e32 v132, 0x3f4c422a, v132
	v_add_f32_e32 v132, v132, v132
	v_mul_f32_e32 v132, 0x3fb8aa3b, v132
	v_exp_f32_e32 v132, v132
	v_mul_f32_e32 v133, 0.5, v177
	v_add_f32_e32 v132, 1.0, v132
	v_div_scale_f32 v134, s[100:101], v132, v132, 2.0
	v_rcp_f32_e32 v135, v134
	s_nop 0
	v_fma_f32 v136, -v134, v135, 1.0
	v_fmac_f32_e32 v135, v136, v135
	v_div_scale_f32 v136, vcc, 2.0, v132, 2.0
	v_mul_f32_e32 v137, v136, v135
	v_fma_f32 v138, -v134, v137, v136
	v_fmac_f32_e32 v137, v138, v135
	v_fma_f32 v134, -v134, v137, v136
	v_div_fmas_f32 v134, v134, v135, v137
	v_div_fixup_f32 v132, v134, v132, 2.0
	v_sub_f32_e32 v132, 1.0, v132
	v_add_f32_e32 v132, 1.0, v132
	v_mul_f32_e32 v132, v133, v132
	v_bfe_u32 v133, v132, 16, 1
	v_add3_u32 v132, v132, v133, s27
	v_add_u32_e32 v184, s92, v184
	global_store_short_d16_hi v184, v132, s[48:49]
	s_nop 0
	v_fmac_f32_e32 v178, v164, v169
	v_mul_f32_e32 v132, 0x3d372713, v178
	v_mul_f32_e32 v132, v178, v132
	v_fma_f32 v132, v178, v132, v178
	v_mul_f32_e32 v132, 0x3f4c422a, v132
	v_add_f32_e32 v132, v132, v132
	v_mul_f32_e32 v132, 0x3fb8aa3b, v132
	v_exp_f32_e32 v132, v132
	v_mul_f32_e32 v133, 0.5, v178
	v_add_f32_e32 v132, 1.0, v132
	v_div_scale_f32 v134, s[100:101], v132, v132, 2.0
	v_rcp_f32_e32 v135, v134
	s_nop 0
	v_fma_f32 v136, -v134, v135, 1.0
	v_fmac_f32_e32 v135, v136, v135
	v_div_scale_f32 v136, vcc, 2.0, v132, 2.0
	v_mul_f32_e32 v137, v136, v135
	v_fma_f32 v138, -v134, v137, v136
	v_fmac_f32_e32 v137, v138, v135
	v_fma_f32 v134, -v134, v137, v136
	v_div_fmas_f32 v134, v134, v135, v137
	v_div_fixup_f32 v132, v134, v132, 2.0
	v_sub_f32_e32 v132, 1.0, v132
	v_add_f32_e32 v132, 1.0, v132
	v_mul_f32_e32 v132, v133, v132
	v_bfe_u32 v133, v132, 16, 1
	v_add3_u32 v132, v132, v133, s27
	v_add_u32_e32 v184, s34, v18
	global_store_short_d16_hi v184, v132, s[48:49]
	s_nop 0
	v_fmac_f32_e32 v179, v164, v170
	v_mul_f32_e32 v132, 0x3d372713, v179
	v_mul_f32_e32 v132, v179, v132
	v_fma_f32 v132, v179, v132, v179
	v_mul_f32_e32 v132, 0x3f4c422a, v132
	v_add_f32_e32 v132, v132, v132
	v_mul_f32_e32 v132, 0x3fb8aa3b, v132
	v_exp_f32_e32 v132, v132
	v_mul_f32_e32 v133, 0.5, v179
	v_add_f32_e32 v132, 1.0, v132
	v_div_scale_f32 v134, s[100:101], v132, v132, 2.0
	v_rcp_f32_e32 v135, v134
	s_nop 0
	v_fma_f32 v136, -v134, v135, 1.0
	v_fmac_f32_e32 v135, v136, v135
	v_div_scale_f32 v136, vcc, 2.0, v132, 2.0
	v_mul_f32_e32 v137, v136, v135
	v_fma_f32 v138, -v134, v137, v136
	v_fmac_f32_e32 v137, v138, v135
	v_fma_f32 v134, -v134, v137, v136
	v_div_fmas_f32 v134, v134, v135, v137
	v_div_fixup_f32 v132, v134, v132, 2.0
	v_sub_f32_e32 v132, 1.0, v132
	v_add_f32_e32 v132, 1.0, v132
	v_mul_f32_e32 v132, v133, v132
	v_bfe_u32 v133, v132, 16, 1
	v_add3_u32 v132, v132, v133, s27
	v_add_u32_e32 v184, s92, v184
	global_store_short_d16_hi v184, v132, s[48:49]
	s_nop 0
	v_fmac_f32_e32 v180, v164, v171
	v_mul_f32_e32 v132, 0x3d372713, v180
	v_mul_f32_e32 v132, v180, v132
	v_fma_f32 v132, v180, v132, v180
	v_mul_f32_e32 v132, 0x3f4c422a, v132
	v_add_f32_e32 v132, v132, v132
	v_mul_f32_e32 v132, 0x3fb8aa3b, v132
	v_exp_f32_e32 v132, v132
	v_mul_f32_e32 v133, 0.5, v180
	v_add_f32_e32 v132, 1.0, v132
	v_div_scale_f32 v134, s[100:101], v132, v132, 2.0
	v_rcp_f32_e32 v135, v134
	s_nop 0
	v_fma_f32 v136, -v134, v135, 1.0
	v_fmac_f32_e32 v135, v136, v135
	v_div_scale_f32 v136, vcc, 2.0, v132, 2.0
	v_mul_f32_e32 v137, v136, v135
	v_fma_f32 v138, -v134, v137, v136
	v_fmac_f32_e32 v137, v138, v135
	v_fma_f32 v134, -v134, v137, v136
	v_div_fmas_f32 v134, v134, v135, v137
	v_div_fixup_f32 v132, v134, v132, 2.0
	v_sub_f32_e32 v132, 1.0, v132
	v_add_f32_e32 v132, 1.0, v132
	v_mul_f32_e32 v132, v133, v132
	v_bfe_u32 v133, v132, 16, 1
	v_add3_u32 v132, v132, v133, s27
	v_add_u32_e32 v184, s92, v184
	global_store_short_d16_hi v184, v132, s[48:49]
	s_nop 0
	v_fmac_f32_e32 v181, v164, v172
	v_mul_f32_e32 v132, 0x3d372713, v181
	v_mul_f32_e32 v132, v181, v132
	v_fma_f32 v132, v181, v132, v181
	v_mul_f32_e32 v132, 0x3f4c422a, v132
	v_add_f32_e32 v132, v132, v132
	v_mul_f32_e32 v132, 0x3fb8aa3b, v132
	v_exp_f32_e32 v132, v132
	v_mul_f32_e32 v133, 0.5, v181
	v_add_f32_e32 v132, 1.0, v132
	v_div_scale_f32 v134, s[100:101], v132, v132, 2.0
	v_rcp_f32_e32 v135, v134
	s_nop 0
	v_fma_f32 v136, -v134, v135, 1.0
	v_fmac_f32_e32 v135, v136, v135
	v_div_scale_f32 v136, vcc, 2.0, v132, 2.0
	v_mul_f32_e32 v137, v136, v135
	v_fma_f32 v138, -v134, v137, v136
	v_fmac_f32_e32 v137, v138, v135
	v_fma_f32 v134, -v134, v137, v136
	v_div_fmas_f32 v134, v134, v135, v137
	v_div_fixup_f32 v132, v134, v132, 2.0
	v_sub_f32_e32 v132, 1.0, v132
	v_add_f32_e32 v132, 1.0, v132
	v_mul_f32_e32 v132, v133, v132
	v_bfe_u32 v133, v132, 16, 1
	v_add3_u32 v132, v132, v133, s27
	v_add_u32_e32 v184, s92, v184
	global_store_short_d16_hi v184, v132, s[48:49]
	s_nop 0
	s_sub_u32 s43, s43, 1
	s_cmp_eq_u32 s43, 0
	s_cbranch_scc1 .Ls5o_done
	s_mov_b32 s100, s41
	s_branch .Ls5o_task

.Lsp3_cctx:
	s_add_u32 s35, s63, 0x80
	v_and_b32_e32 v228, 63, v206
	v_lshrrev_b32_e32 v229, 6, v206
	v_and_b32_e32 v0, 15, v228
	v_readfirstlane_b32 s40, v229
	v_lshrrev_b32_e32 v1, 4, v228
	s_sub_u32 s38, s35, 0x80
	s_and_b32 s42, s40, 3
	s_lshr_b32 s43, s40, 2
	s_lshl_b32 s43, s43, 2
	s_lshr_b32 s100, s38, 4
	s_lshl_b32 s101, s100, 1
	s_bfe_u32 s41, s38, 0x30001
	s_and_b32 s39, s38, 1
	s_lshl_b32 s52, s100, 1
	s_add_u32 s52, s52, s36
	s_lshl_b32 s52, s52, 1
	s_add_u32 s52, s52, s39
	s_lshl_b32 s52, s52, 3
	s_add_u32 s52, s52, s41
	s_add_u32 s100, s101, 1
	s_cmp_eq_u32 s39, 0
	s_cselect_b32 s101, s101, s100
	s_cselect_b32 s92, 0, -1
	s_mov_b32 s98, 0xfffe0000
	s_cselect_b32 s98, 0x20000, s98
	s_mov_b32 s99, 0xffff0000
	s_cselect_b32 s99, 0x10000, s99
	s_mov_b32 s50, 0xfffc0000
	s_cselect_b32 s50, 0x40000, s50
	s_mov_b32 s51, 0xffffe000
	s_cselect_b32 s51, 0x2000, s51
	s_lshl_b32 s100, s101, 3
	s_add_u32 s100, s100, s41
	s_lshl_b32 s100, s100, 14
	s_lshl_b32 s53, s42, 12
	s_add_u32 s100, s100, s53
	s_add_u32 s100, s100, 0xc184000
	s_add_u32 s44, s96, s100
	s_addc_u32 s45, s97, 0
	s_lshl_b32 s100, s101, 1
	s_lshr_b32 s53, s41, 2
	s_add_u32 s100, s100, s53
	s_lshl_b32 s100, s100, 15
	s_lshl_b32 s53, s43, 12
	s_add_u32 s100, s100, s53
	s_add_u32 s100, s100, 0xbe84000
	s_add_u32 s46, s96, s100
	s_addc_u32 s47, s97, 0
	s_lshl_b32 s100, s101, 1
	s_add_u32 s100, s100, s39
	s_lshl_b32 s100, s100, 3
	s_add_u32 s100, s100, s41
	s_lshl_b32 s53, s100, 14
	s_lshl_b32 s59, s42, 12
	s_add_u32 s53, s53, s59
	s_lshl_b32 s59, s43, 5
	s_add_u32 s53, s53, s59
	s_add_u32 s53, s53, 0xac84000
	s_add_u32 s48, s96, s53
	s_addc_u32 s49, s97, 0
	s_lshl_b32 s100, s100, 9
	s_add_u32 s53, s100, 0xcae4000
	s_add_u32 s58, s96, s53
	s_addc_u32 s59, s97, 0
	s_cmp_eq_u32 s39, 0
	s_cselect_b32 s53, 0x1fc, 0
	s_add_u32 s58, s58, s53
	s_addc_u32 s59, s59, 0
	global_load_dword v227, v2, s[58:59]
	s_add_u32 s58, s58, s51
	s_addc_u32 s59, s59, s92
	global_load_dword v232, v2, s[58:59]
	s_add_u32 s53, s100, 0xcb44000
	s_add_u32 s58, s96, s53
	s_addc_u32 s59, s97, 0
	s_cmp_eq_u32 s39, 0
	s_cbranch_scc1 .Lch_sctx_fw
	s_sub_u32 s58, s58, 0x2000
	s_subb_u32 s59, s59, 0
.Lch_sctx_fw:
	v_lshrrev_b32_e32 v230, 5, v228
	v_and_b32_e32 v231, 31, v228
	v_lshlrev_b32_e32 v230, 13, v230
	v_lshl_add_u32 v230, v231, 4, v230
	s_mul_i32 s53, s40, 16896
	s_lshl_b32 s100, s51, 1
	s_add_u32 m0, s53, 0x0
	s_nop 0
	global_load_lds_dwordx4 v230, s[58:59]
	v_lshlrev_b32_e32 v3, 8, v0
	v_lshl_add_u32 v3, v1, 4, v3
	v_add_u32_e32 v197, 0x1000, v3
	v_add_u32_e32 v199, 0x2000, v3
	v_add_u32_e32 v204, 0x3000, v3
	v_lshlrev_b32_e32 v205, 11, v1
	v_lshl_add_u32 v205, v0, 2, v205
	v_lshrrev_b32_e32 v221, 1, v205
	v_lshl_add_u32 v226, v1, 5, s53
	v_mov_b32_e32 v188, 0
	v_mov_b32_e32 v189, 0
	v_mov_b32_e32 v190, 0
	v_mov_b32_e32 v191, 0
	v_mov_b32_e32 v192, 0
	v_mov_b32_e32 v193, 0
	v_mov_b32_e32 v194, 0
	v_mov_b32_e32 v195, 0
	v_mov_b32_e32 v200, 0
	v_mov_b32_e32 v201, 0
	v_mov_b32_e32 v202, 0
	v_mov_b32_e32 v203, 0
	v_mov_b32_e32 v222, 0
	v_mov_b32_e32 v223, 0
	v_mov_b32_e32 v224, 0
	v_mov_b32_e32 v225, 0
	global_load_dwordx4 v[4:7], v3, s[44:45]
	global_load_dwordx4 v[8:11], v3, s[44:45] offset:64
	global_load_dwordx4 v[12:15], v3, s[44:45] offset:128
	global_load_dwordx4 v[16:19], v3, s[44:45] offset:192
	global_load_dwordx4 v[20:23], v3, s[46:47]
	global_load_dwordx4 v[24:27], v197, s[46:47]
	global_load_dwordx4 v[28:31], v199, s[46:47]
	global_load_dwordx4 v[32:35], v204, s[46:47]
	global_load_dwordx4 v[36:39], v3, s[46:47] offset:64
	global_load_dwordx4 v[40:43], v197, s[46:47] offset:64
	global_load_dwordx4 v[44:47], v199, s[46:47] offset:64
	global_load_dwordx4 v[48:51], v204, s[46:47] offset:64
	global_load_dwordx4 v[52:55], v3, s[46:47] offset:128
	global_load_dwordx4 v[56:59], v197, s[46:47] offset:128
	global_load_dwordx4 v[60:63], v199, s[46:47] offset:128
	global_load_dwordx4 v[64:67], v204, s[46:47] offset:128
	global_load_dwordx4 v[68:71], v3, s[46:47] offset:192
	global_load_dwordx4 v[72:75], v197, s[46:47] offset:192
	global_load_dwordx4 v[76:79], v199, s[46:47] offset:192
	global_load_dwordx4 v[80:83], v204, s[46:47] offset:192
	s_add_u32 s44, s44, s98
	s_addc_u32 s45, s45, s92
	s_add_u32 s46, s46, s99
	s_addc_u32 s47, s47, s92
	global_load_dwordx4 v[84:87], v3, s[44:45]
	global_load_dwordx4 v[88:91], v3, s[44:45] offset:64
	global_load_dwordx4 v[92:95], v3, s[44:45] offset:128
	global_load_dwordx4 v[96:99], v3, s[44:45] offset:192
	global_load_dwordx4 v[100:103], v3, s[46:47]
	global_load_dwordx4 v[104:107], v197, s[46:47]
	global_load_dwordx4 v[108:111], v199, s[46:47]
	global_load_dwordx4 v[112:115], v204, s[46:47]
	global_load_dwordx4 v[116:119], v3, s[46:47] offset:64
	global_load_dwordx4 v[120:123], v197, s[46:47] offset:64
	global_load_dwordx4 v[124:127], v199, s[46:47] offset:64
	global_load_dwordx4 v[128:131], v204, s[46:47] offset:64
	global_load_dwordx4 v[132:135], v3, s[46:47] offset:128
	global_load_dwordx4 v[136:139], v197, s[46:47] offset:128
	global_load_dwordx4 v[140:143], v199, s[46:47] offset:128
	global_load_dwordx4 v[144:147], v204, s[46:47] offset:128
	global_load_dwordx4 v[148:151], v3, s[46:47] offset:192
	global_load_dwordx4 v[152:155], v197, s[46:47] offset:192
	global_load_dwordx4 v[156:159], v199, s[46:47] offset:192
	global_load_dwordx4 v[160:163], v204, s[46:47] offset:192
	s_add_u32 s44, s44, s98
	s_addc_u32 s45, s45, s92
	s_add_u32 s46, s46, s99
	s_addc_u32 s47, s47, s92
	s_waitcnt vmcnt(20)
	s_xor_b32 s100, s39, 0
	s_lshl_b32 s100, s100, 9
	v_add_u32_e32 v233, s100, v226
	s_nop 0
	ds_read_b128 v[164:167], v233
	ds_read_b128 v[168:171], v233 offset:16
	v_bfe_u32 v228, v188, 16, 1
	v_add3_u32 v228, v188, v228, s27
	global_store_short_d16_hi v221, v228, s[48:49] offset:0
	v_bfe_u32 v229, v189, 16, 1
	v_add3_u32 v229, v189, v229, s27
	global_store_short_d16_hi v221, v229, s[48:49] offset:256
	v_bfe_u32 v230, v190, 16, 1
	v_add3_u32 v230, v190, v230, s27
	global_store_short_d16_hi v221, v230, s[48:49] offset:512
	v_bfe_u32 v231, v191, 16, 1
	v_add3_u32 v231, v191, v231, s27
	global_store_short_d16_hi v221, v231, s[48:49] offset:768
	v_bfe_u32 v228, v192, 16, 1
	v_add3_u32 v228, v192, v228, s27
	global_store_short_d16_hi v221, v228, s[48:49] offset:32
	v_bfe_u32 v229, v193, 16, 1
	v_add3_u32 v229, v193, v229, s27
	global_store_short_d16_hi v221, v229, s[48:49] offset:288
	v_bfe_u32 v230, v194, 16, 1
	v_add3_u32 v230, v194, v230, s27
	global_store_short_d16_hi v221, v230, s[48:49] offset:544
	v_bfe_u32 v231, v195, 16, 1
	v_add3_u32 v231, v195, v231, s27
	global_store_short_d16_hi v221, v231, s[48:49] offset:800
	v_bfe_u32 v228, v200, 16, 1
	v_add3_u32 v228, v200, v228, s27
	global_store_short_d16_hi v221, v228, s[48:49] offset:64
	v_bfe_u32 v229, v201, 16, 1
	v_add3_u32 v229, v201, v229, s27
	global_store_short_d16_hi v221, v229, s[48:49] offset:320
	v_bfe_u32 v230, v202, 16, 1
	v_add3_u32 v230, v202, v230, s27
	global_store_short_d16_hi v221, v230, s[48:49] offset:576
	v_bfe_u32 v231, v203, 16, 1
	v_add3_u32 v231, v203, v231, s27
	global_store_short_d16_hi v221, v231, s[48:49] offset:832
	v_bfe_u32 v228, v222, 16, 1
	v_add3_u32 v228, v222, v228, s27
	global_store_short_d16_hi v221, v228, s[48:49] offset:96
	v_bfe_u32 v229, v223, 16, 1
	v_add3_u32 v229, v223, v229, s27
	global_store_short_d16_hi v221, v229, s[48:49] offset:352
	v_bfe_u32 v230, v224, 16, 1
	v_add3_u32 v230, v224, v230, s27
	global_store_short_d16_hi v221, v230, s[48:49] offset:608
	v_bfe_u32 v231, v225, 16, 1
	v_add3_u32 v231, v225, v231, s27
	global_store_short_d16_hi v221, v231, s[48:49] offset:864
	s_add_u32 s48, s48, s50
	s_addc_u32 s49, s49, s92
	v_mul_f32_e32 v227, 0x3fb8aa3b, v227
	v_exp_f32_e32 v227, v227
	s_nop 0
	v_mul_f32_e32 v188, v188, v227
	v_mul_f32_e32 v189, v189, v227
	v_mul_f32_e32 v190, v190, v227
	v_mul_f32_e32 v191, v191, v227
	v_mul_f32_e32 v192, v192, v227
	v_mul_f32_e32 v193, v193, v227
	v_mul_f32_e32 v194, v194, v227
	v_mul_f32_e32 v195, v195, v227
	v_mul_f32_e32 v200, v200, v227
	v_mul_f32_e32 v201, v201, v227
	v_mul_f32_e32 v202, v202, v227
	v_mul_f32_e32 v203, v203, v227
	v_mul_f32_e32 v222, v222, v227
	v_mul_f32_e32 v223, v223, v227
	v_mul_f32_e32 v224, v224, v227
	v_mul_f32_e32 v225, v225, v227
	ds_read_b128 v[172:175], v233 offset:128
	ds_read_b128 v[176:179], v233 offset:144
	s_waitcnt lgkmcnt(2)
	v_lshlrev_b32_e32 v228, 16, v4
	v_and_b32_e32 v229, s28, v4
	v_mul_f32_e32 v228, v228, v164
	v_mul_f32_e32 v229, v229, v165
	v_cvt_pk_bf16_f32 v180, v228, v229
	v_lshlrev_b32_e32 v228, 16, v5
	v_and_b32_e32 v229, s28, v5
	v_mul_f32_e32 v228, v228, v166
	v_mul_f32_e32 v229, v229, v167
	v_cvt_pk_bf16_f32 v181, v228, v229
	v_lshlrev_b32_e32 v228, 16, v6
	v_and_b32_e32 v229, s28, v6
	v_mul_f32_e32 v228, v228, v168
	v_mul_f32_e32 v229, v229, v169
	v_cvt_pk_bf16_f32 v182, v228, v229
	v_lshlrev_b32_e32 v228, 16, v7
	v_and_b32_e32 v229, s28, v7
	v_mul_f32_e32 v228, v228, v170
	v_mul_f32_e32 v229, v229, v171
	v_cvt_pk_bf16_f32 v183, v228, v229
	s_nop 1
	v_mfma_f32_16x16x32_bf16 v[188:191], v[180:183], v[20:23], v[188:191]
	v_mfma_f32_16x16x32_bf16 v[192:195], v[180:183], v[24:27], v[192:195]
	v_mfma_f32_16x16x32_bf16 v[200:203], v[180:183], v[28:31], v[200:203]
	v_mfma_f32_16x16x32_bf16 v[222:225], v[180:183], v[32:35], v[222:225]
	ds_read_b128 v[164:167], v233 offset:256
	ds_read_b128 v[168:171], v233 offset:272
	s_waitcnt lgkmcnt(2)
	v_lshlrev_b32_e32 v228, 16, v8
	v_and_b32_e32 v229, s28, v8
	v_mul_f32_e32 v228, v228, v172
	v_mul_f32_e32 v229, v229, v173
	v_cvt_pk_bf16_f32 v184, v228, v229
	v_lshlrev_b32_e32 v228, 16, v9
	v_and_b32_e32 v229, s28, v9
	v_mul_f32_e32 v228, v228, v174
	v_mul_f32_e32 v229, v229, v175
	v_cvt_pk_bf16_f32 v185, v228, v229
	v_lshlrev_b32_e32 v228, 16, v10
	v_and_b32_e32 v229, s28, v10
	v_mul_f32_e32 v228, v228, v176
	v_mul_f32_e32 v229, v229, v177
	v_cvt_pk_bf16_f32 v186, v228, v229
	v_lshlrev_b32_e32 v228, 16, v11
	v_and_b32_e32 v229, s28, v11
	v_mul_f32_e32 v228, v228, v178
	v_mul_f32_e32 v229, v229, v179
	v_cvt_pk_bf16_f32 v187, v228, v229
	s_nop 1
	v_mfma_f32_16x16x32_bf16 v[188:191], v[184:187], v[36:39], v[188:191]
	v_mfma_f32_16x16x32_bf16 v[192:195], v[184:187], v[40:43], v[192:195]
	v_mfma_f32_16x16x32_bf16 v[200:203], v[184:187], v[44:47], v[200:203]
	v_mfma_f32_16x16x32_bf16 v[222:225], v[184:187], v[48:51], v[222:225]
	ds_read_b128 v[172:175], v233 offset:384
	ds_read_b128 v[176:179], v233 offset:400
	s_waitcnt lgkmcnt(2)
	v_lshlrev_b32_e32 v228, 16, v12
	v_and_b32_e32 v229, s28, v12
	v_mul_f32_e32 v228, v228, v164
	v_mul_f32_e32 v229, v229, v165
	v_cvt_pk_bf16_f32 v180, v228, v229
	v_lshlrev_b32_e32 v228, 16, v13
	v_and_b32_e32 v229, s28, v13
	v_mul_f32_e32 v228, v228, v166
	v_mul_f32_e32 v229, v229, v167
	v_cvt_pk_bf16_f32 v181, v228, v229
	v_lshlrev_b32_e32 v228, 16, v14
	v_and_b32_e32 v229, s28, v14
	v_mul_f32_e32 v228, v228, v168
	v_mul_f32_e32 v229, v229, v169
	v_cvt_pk_bf16_f32 v182, v228, v229
	v_lshlrev_b32_e32 v228, 16, v15
	v_and_b32_e32 v229, s28, v15
	v_mul_f32_e32 v228, v228, v170
	v_mul_f32_e32 v229, v229, v171
	v_cvt_pk_bf16_f32 v183, v228, v229
	s_nop 1
	v_mfma_f32_16x16x32_bf16 v[188:191], v[180:183], v[52:55], v[188:191]
	v_mfma_f32_16x16x32_bf16 v[192:195], v[180:183], v[56:59], v[192:195]
	v_mfma_f32_16x16x32_bf16 v[200:203], v[180:183], v[60:63], v[200:203]
	v_mfma_f32_16x16x32_bf16 v[222:225], v[180:183], v[64:67], v[222:225]
	s_waitcnt lgkmcnt(0)
	v_lshlrev_b32_e32 v228, 16, v16
	v_and_b32_e32 v229, s28, v16
	v_mul_f32_e32 v228, v228, v172
	v_mul_f32_e32 v229, v229, v173
	v_cvt_pk_bf16_f32 v184, v228, v229
	v_lshlrev_b32_e32 v228, 16, v17
	v_and_b32_e32 v229, s28, v17
	v_mul_f32_e32 v228, v228, v174
	v_mul_f32_e32 v229, v229, v175
	v_cvt_pk_bf16_f32 v185, v228, v229
	v_lshlrev_b32_e32 v228, 16, v18
	v_and_b32_e32 v229, s28, v18
	v_mul_f32_e32 v228, v228, v176
	v_mul_f32_e32 v229, v229, v177
	v_cvt_pk_bf16_f32 v186, v228, v229
	v_lshlrev_b32_e32 v228, 16, v19
	v_and_b32_e32 v229, s28, v19
	v_mul_f32_e32 v228, v228, v178
	v_mul_f32_e32 v229, v229, v179
	v_cvt_pk_bf16_f32 v187, v228, v229
	s_nop 1
	v_mfma_f32_16x16x32_bf16 v[188:191], v[184:187], v[68:71], v[188:191]
	v_mfma_f32_16x16x32_bf16 v[192:195], v[184:187], v[72:75], v[192:195]
	v_mfma_f32_16x16x32_bf16 v[200:203], v[184:187], v[76:79], v[200:203]
	v_mfma_f32_16x16x32_bf16 v[222:225], v[184:187], v[80:83], v[222:225]
	s_nop 7
	s_waitcnt vmcnt(16)
	s_xor_b32 s100, s39, 1
	s_lshl_b32 s100, s100, 9
	v_add_u32_e32 v233, s100, v226
	s_nop 0
	ds_read_b128 v[164:167], v233
	ds_read_b128 v[168:171], v233 offset:16
	v_bfe_u32 v228, v188, 16, 1
	v_add3_u32 v228, v188, v228, s27
	global_store_short_d16_hi v221, v228, s[48:49] offset:0
	v_bfe_u32 v229, v189, 16, 1
	v_add3_u32 v229, v189, v229, s27
	global_store_short_d16_hi v221, v229, s[48:49] offset:256
	v_bfe_u32 v230, v190, 16, 1
	v_add3_u32 v230, v190, v230, s27
	global_store_short_d16_hi v221, v230, s[48:49] offset:512
	v_bfe_u32 v231, v191, 16, 1
	v_add3_u32 v231, v191, v231, s27
	global_store_short_d16_hi v221, v231, s[48:49] offset:768
	v_bfe_u32 v228, v192, 16, 1
	v_add3_u32 v228, v192, v228, s27
	global_store_short_d16_hi v221, v228, s[48:49] offset:32
	v_bfe_u32 v229, v193, 16, 1
	v_add3_u32 v229, v193, v229, s27
	global_store_short_d16_hi v221, v229, s[48:49] offset:288
	v_bfe_u32 v230, v194, 16, 1
	v_add3_u32 v230, v194, v230, s27
	global_store_short_d16_hi v221, v230, s[48:49] offset:544
	v_bfe_u32 v231, v195, 16, 1
	v_add3_u32 v231, v195, v231, s27
	global_store_short_d16_hi v221, v231, s[48:49] offset:800
	v_bfe_u32 v228, v200, 16, 1
	v_add3_u32 v228, v200, v228, s27
	global_store_short_d16_hi v221, v228, s[48:49] offset:64
	v_bfe_u32 v229, v201, 16, 1
	v_add3_u32 v229, v201, v229, s27
	global_store_short_d16_hi v221, v229, s[48:49] offset:320
	v_bfe_u32 v230, v202, 16, 1
	v_add3_u32 v230, v202, v230, s27
	global_store_short_d16_hi v221, v230, s[48:49] offset:576
	v_bfe_u32 v231, v203, 16, 1
	v_add3_u32 v231, v203, v231, s27
	global_store_short_d16_hi v221, v231, s[48:49] offset:832
	v_bfe_u32 v228, v222, 16, 1
	v_add3_u32 v228, v222, v228, s27
	global_store_short_d16_hi v221, v228, s[48:49] offset:96
	v_bfe_u32 v229, v223, 16, 1
	v_add3_u32 v229, v223, v229, s27
	global_store_short_d16_hi v221, v229, s[48:49] offset:352
	v_bfe_u32 v230, v224, 16, 1
	v_add3_u32 v230, v224, v230, s27
	global_store_short_d16_hi v221, v230, s[48:49] offset:608
	v_bfe_u32 v231, v225, 16, 1
	v_add3_u32 v231, v225, v231, s27
	global_store_short_d16_hi v221, v231, s[48:49] offset:864
	s_add_u32 s48, s48, s50
	s_addc_u32 s49, s49, s92
	v_mul_f32_e32 v227, 0x3fb8aa3b, v232
	v_exp_f32_e32 v227, v227
	s_nop 0
	v_mul_f32_e32 v188, v188, v227
	v_mul_f32_e32 v189, v189, v227
	v_mul_f32_e32 v190, v190, v227
	v_mul_f32_e32 v191, v191, v227
	v_mul_f32_e32 v192, v192, v227
	v_mul_f32_e32 v193, v193, v227
	v_mul_f32_e32 v194, v194, v227
	v_mul_f32_e32 v195, v195, v227
	v_mul_f32_e32 v200, v200, v227
	v_mul_f32_e32 v201, v201, v227
	v_mul_f32_e32 v202, v202, v227
	v_mul_f32_e32 v203, v203, v227
	v_mul_f32_e32 v222, v222, v227
	v_mul_f32_e32 v223, v223, v227
	v_mul_f32_e32 v224, v224, v227
	v_mul_f32_e32 v225, v225, v227
	ds_read_b128 v[172:175], v233 offset:128
	ds_read_b128 v[176:179], v233 offset:144
	s_waitcnt lgkmcnt(2)
	v_lshlrev_b32_e32 v228, 16, v84
	v_and_b32_e32 v229, s28, v84
	v_mul_f32_e32 v228, v228, v164
	v_mul_f32_e32 v229, v229, v165
	v_cvt_pk_bf16_f32 v180, v228, v229
	v_lshlrev_b32_e32 v228, 16, v85
	v_and_b32_e32 v229, s28, v85
	v_mul_f32_e32 v228, v228, v166
	v_mul_f32_e32 v229, v229, v167
	v_cvt_pk_bf16_f32 v181, v228, v229
	v_lshlrev_b32_e32 v228, 16, v86
	v_and_b32_e32 v229, s28, v86
	v_mul_f32_e32 v228, v228, v168
	v_mul_f32_e32 v229, v229, v169
	v_cvt_pk_bf16_f32 v182, v228, v229
	v_lshlrev_b32_e32 v228, 16, v87
	v_and_b32_e32 v229, s28, v87
	v_mul_f32_e32 v228, v228, v170
	v_mul_f32_e32 v229, v229, v171
	v_cvt_pk_bf16_f32 v183, v228, v229
	s_nop 1
	v_mfma_f32_16x16x32_bf16 v[188:191], v[180:183], v[100:103], v[188:191]
	v_mfma_f32_16x16x32_bf16 v[192:195], v[180:183], v[104:107], v[192:195]
	v_mfma_f32_16x16x32_bf16 v[200:203], v[180:183], v[108:111], v[200:203]
	v_mfma_f32_16x16x32_bf16 v[222:225], v[180:183], v[112:115], v[222:225]
	ds_read_b128 v[164:167], v233 offset:256
	ds_read_b128 v[168:171], v233 offset:272
	s_waitcnt lgkmcnt(2)
	v_lshlrev_b32_e32 v228, 16, v88
	v_and_b32_e32 v229, s28, v88
	v_mul_f32_e32 v228, v228, v172
	v_mul_f32_e32 v229, v229, v173
	v_cvt_pk_bf16_f32 v184, v228, v229
	v_lshlrev_b32_e32 v228, 16, v89
	v_and_b32_e32 v229, s28, v89
	v_mul_f32_e32 v228, v228, v174
	v_mul_f32_e32 v229, v229, v175
	v_cvt_pk_bf16_f32 v185, v228, v229
	v_lshlrev_b32_e32 v228, 16, v90
	v_and_b32_e32 v229, s28, v90
	v_mul_f32_e32 v228, v228, v176
	v_mul_f32_e32 v229, v229, v177
	v_cvt_pk_bf16_f32 v186, v228, v229
	v_lshlrev_b32_e32 v228, 16, v91
	v_and_b32_e32 v229, s28, v91
	v_mul_f32_e32 v228, v228, v178
	v_mul_f32_e32 v229, v229, v179
	v_cvt_pk_bf16_f32 v187, v228, v229
	s_nop 1
	v_mfma_f32_16x16x32_bf16 v[188:191], v[184:187], v[116:119], v[188:191]
	v_mfma_f32_16x16x32_bf16 v[192:195], v[184:187], v[120:123], v[192:195]
	v_mfma_f32_16x16x32_bf16 v[200:203], v[184:187], v[124:127], v[200:203]
	v_mfma_f32_16x16x32_bf16 v[222:225], v[184:187], v[128:131], v[222:225]
	ds_read_b128 v[172:175], v233 offset:384
	ds_read_b128 v[176:179], v233 offset:400
	s_waitcnt lgkmcnt(2)
	v_lshlrev_b32_e32 v228, 16, v92
	v_and_b32_e32 v229, s28, v92
	v_mul_f32_e32 v228, v228, v164
	v_mul_f32_e32 v229, v229, v165
	v_cvt_pk_bf16_f32 v180, v228, v229
	v_lshlrev_b32_e32 v228, 16, v93
	v_and_b32_e32 v229, s28, v93
	v_mul_f32_e32 v228, v228, v166
	v_mul_f32_e32 v229, v229, v167
	v_cvt_pk_bf16_f32 v181, v228, v229
	v_lshlrev_b32_e32 v228, 16, v94
	v_and_b32_e32 v229, s28, v94
	v_mul_f32_e32 v228, v228, v168
	v_mul_f32_e32 v229, v229, v169
	v_cvt_pk_bf16_f32 v182, v228, v229
	v_lshlrev_b32_e32 v228, 16, v95
	v_and_b32_e32 v229, s28, v95
	v_mul_f32_e32 v228, v228, v170
	v_mul_f32_e32 v229, v229, v171
	v_cvt_pk_bf16_f32 v183, v228, v229
	s_nop 1
	v_mfma_f32_16x16x32_bf16 v[188:191], v[180:183], v[132:135], v[188:191]
	v_mfma_f32_16x16x32_bf16 v[192:195], v[180:183], v[136:139], v[192:195]
	v_mfma_f32_16x16x32_bf16 v[200:203], v[180:183], v[140:143], v[200:203]
	v_mfma_f32_16x16x32_bf16 v[222:225], v[180:183], v[144:147], v[222:225]
	s_waitcnt lgkmcnt(0)
	v_lshlrev_b32_e32 v228, 16, v96
	v_and_b32_e32 v229, s28, v96
	v_mul_f32_e32 v228, v228, v172
	v_mul_f32_e32 v229, v229, v173
	v_cvt_pk_bf16_f32 v184, v228, v229
	v_lshlrev_b32_e32 v228, 16, v97
	v_and_b32_e32 v229, s28, v97
	v_mul_f32_e32 v228, v228, v174
	v_mul_f32_e32 v229, v229, v175
	v_cvt_pk_bf16_f32 v185, v228, v229
	v_lshlrev_b32_e32 v228, 16, v98
	v_and_b32_e32 v229, s28, v98
	v_mul_f32_e32 v228, v228, v176
	v_mul_f32_e32 v229, v229, v177
	v_cvt_pk_bf16_f32 v186, v228, v229
	v_lshlrev_b32_e32 v228, 16, v99
	v_and_b32_e32 v229, s28, v99
	v_mul_f32_e32 v228, v228, v178
	v_mul_f32_e32 v229, v229, v179
	v_cvt_pk_bf16_f32 v187, v228, v229
	s_nop 1
	v_mfma_f32_16x16x32_bf16 v[188:191], v[184:187], v[148:151], v[188:191]
	v_mfma_f32_16x16x32_bf16 v[192:195], v[184:187], v[152:155], v[192:195]
	v_mfma_f32_16x16x32_bf16 v[200:203], v[184:187], v[156:159], v[200:203]
	v_mfma_f32_16x16x32_bf16 v[222:225], v[184:187], v[160:163], v[222:225]
	s_nop 7
	v_readlane_b32 s58, v237, 7
	v_readlane_b32 s59, v237, 8
	s_lshl_b32 s100, s52, 15
	s_lshl_b32 s53, s42, 13
	s_add_u32 s100, s100, s53
	s_lshl_b32 s53, s43, 6
	s_add_u32 s100, s100, s53
	s_add_u32 s100, s100, 0x1800000
	s_add_u32 s58, s58, s100
	s_addc_u32 s59, s59, 0
	s_nop 3
	global_store_dword v205, v188, s[58:59] offset:0
	global_store_dword v205, v189, s[58:59] offset:512
	global_store_dword v205, v190, s[58:59] offset:1024
	global_store_dword v205, v191, s[58:59] offset:1536
	global_store_dword v205, v192, s[58:59] offset:64
	global_store_dword v205, v193, s[58:59] offset:576
	global_store_dword v205, v194, s[58:59] offset:1088
	global_store_dword v205, v195, s[58:59] offset:1600
	global_store_dword v205, v200, s[58:59] offset:128
	global_store_dword v205, v201, s[58:59] offset:640
	global_store_dword v205, v202, s[58:59] offset:1152
	global_store_dword v205, v203, s[58:59] offset:1664
	global_store_dword v205, v222, s[58:59] offset:192
	global_store_dword v205, v223, s[58:59] offset:704
	global_store_dword v205, v224, s[58:59] offset:1216
	global_store_dword v205, v225, s[58:59] offset:1728
	s_branch .Lsp3_done
.Lsp3_done:
	s_branch .Lsp3_back
.LBB0_157:
	s_mov_b64 s[38:39], 0

.LBB0_568:
	s_or_b64 exec, exec, s[38:39]
	s_waitcnt lgkmcnt(0)
	s_barrier
	ds_read_b32 v0, v208
	s_waitcnt lgkmcnt(0)
	v_readfirstlane_b32 s35, v0
	s_nop 0
	s_add_u32 s35, s35, 0x480
	s_cmp_gt_i32 s35, s13
	s_cbranch_scc1 .LBB0_636
	s_lshl_b32 s4, s36, 2
	s_add_i32 s19, s62, 0xfffffc00
	s_lshl_b32 s5, s36, 1
	s_add_i32 s6, s36, 0xfffffe0
	v_writelane_b32 v234, s6, 0
	s_branch .LBB0_572

.LBB0_571:
	s_or_b64 exec, exec, s[38:39]
	s_waitcnt lgkmcnt(0)
	s_barrier
	ds_read_b32 v0, v208
	s_waitcnt lgkmcnt(0)
	v_readfirstlane_b32 s35, v0
	s_nop 0
	s_add_u32 s35, s35, 0x480
	s_cmp_gt_i32 s35, s13
	s_cbranch_scc1 .LBB0_636

.LBB0_575:
	s_andn2_b64 vcc, exec, s[38:39]
	s_cbranch_vccnz .LBB0_618
.LBB0_618:
	s_mov_b64 s[38:39], 0
.LBB0_619:
	s_andn2_b64 vcc, exec, s[38:39]
	s_cbranch_vccnz .LBB0_633
.LBB0_632:
	v_readlane_b32 s94, v235, 51
	v_readlane_b32 s95, v235, 52
	s_movk_i32 s13, 0x53f
	v_readlane_b32 s61, v235, 55
.LBB0_633:
	s_branch .LBB0_636
.Lsp3_deadlatch:
	v_readlane_b32 s6, v236, 39
	v_readlane_b32 s7, v236, 40
	s_barrier
	s_and_saveexec_b64 s[38:39], s[6:7]
	s_cbranch_execz .LBB0_571
	s_mov_b64 s[42:43], exec
	v_mbcnt_lo_u32_b32 v0, s42, 0
	v_mbcnt_hi_u32_b32 v0, s43, v0
	v_cmp_eq_u32_e32 vcc, 0, v0
	s_and_saveexec_b64 s[40:41], vcc
	s_cbranch_execz .LBB0_570
	s_bcnt1_i32_b64 s35, s[42:43]
	v_readlane_b32 s6, v235, 56
	v_mov_b32_e32 v1, s35
	v_readlane_b32 s7, v235, 57
	s_nop 4
	global_atomic_add v1, v2, v1, s[6:7] sc0
	s_branch .LBB0_570
